# GDN y store issued by lane 0 of each 16-lane row only (exec mask) instead of all 64 lanes
# speedup vs baseline: 1.0090x; 1.0090x over previous
.Lgd2_item:
	s_lshr_b32 s2, s27, 4
	s_and_b32 s3, s27, 15
	s_lshl_b32 s4, s3, 4
	v_lshl_add_u32 v154, v5, 2, s4
	v_lshl_add_u32 v153, v154, 1, v4
	s_and_b32 s4, s3, 3
	s_lshl_b32 s4, s4, 5
	v_lshl_add_u32 v3, v5, 3, s4
	s_and_b32 s4, s3, 12
	s_lshl_b32 s4, s4, 4
	v_min_u32_e32 v155, 15, v198
	v_lshl_add_u32 v104, v155, 2, s4
	s_and_b32 s5, s2, 7
	s_lshl_b32 s3, s5, 7
	s_add_u32 s4, s4, s3
	s_add_u32 s4, s4, 2048
	v_lshl_add_u32 v105, v155, 2, s4
	s_lshr_b32 s4, s2, 3
	v_readlane_b32 s3, v255, 15
	s_mul_i32 s6, s4, 0xc00000
	s_mul_i32 s7, s3, 0x1800
	s_add_u32 s6, s6, s7
	s_lshl_b32 s7, s5, 8
	s_add_u32 s6, s6, s7
	s_add_u32 s6, s6, 0xb38d900
	s_add_u32 s8, s24, s6
	s_addc_u32 s9, s25, 0
	s_lshl_b32 s6, s4, 25
	s_lshl_b32 s7, s3, 14
	s_add_u32 s6, s6, s7
	s_lshl_b32 s7, s5, 7
	s_add_u32 s6, s6, s7
	s_add_u32 s6, s6, 62659584
	s_add_u32 s10, s22, s6
	s_addc_u32 s11, s23, 0
	s_lshl_b32 s6, s4, 18
	s_lshl_b32 s7, s3, 7
	s_add_u32 s6, s6, s7
	s_lshl_b32 s7, s5, 4
	s_add_u32 s6, s6, s7
	s_add_u32 s6, s6, 0x37b8400
	s_add_u32 s12, s22, s6
	s_addc_u32 s13, s23, 0
	s_lshl_b32 s6, s4, 23
	s_lshl_b32 s7, s5, 8
	s_add_u32 s6, s6, s7
	s_add_u32 s6, s6, 333186048
	s_add_u32 s14, s22, s6
	s_addc_u32 s15, s23, 0
	s_movk_i32 s18, 256
	s_movk_i32 s19, 16640
	s_mov_b32 s20, 33024
	v_add_u32_e32 v28, s18, v32
	v_add_u32_e32 v29, s18, v33
	v_add_u32_e32 v30, s18, v34
	v_add_u32_e32 v31, s18, v35
	global_load_dword v108, v36, s[8:9]
	global_load_dword v109, v36, s[8:9] offset:-2048
	global_load_dword v111, v104, s[8:9] offset:2048
	global_load_dword v110, v37, s[10:11]
	global_load_dword v112, v105, s[10:11]
	global_load_dword v113, v106, s[12:13]
	s_add_u32 s8, s8, 0xc000
	s_addc_u32 s9, s9, 0
	s_add_u32 s10, s10, 0x20000
	s_addc_u32 s11, s11, 0
	s_add_u32 s12, s12, 0x400
	s_addc_u32 s13, s13, 0
	s_waitcnt vmcnt(0)
	v_lshlrev_b32_e32 v116, 16, v108
	v_lshlrev_b32_e32 v117, 16, v109
	v_and_b32_e32 v118, s17, v108
	v_and_b32_e32 v119, s17, v109
	v_lshlrev_b32_e32 v120, 16, v110
	v_and_b32_e32 v121, s17, v110
	v_lshlrev_b32_e32 v122, 16, v111
	v_and_b32_e32 v123, s17, v111
	v_lshlrev_b32_e32 v124, 16, v112
	v_and_b32_e32 v125, s17, v112
	ds_write_b128 v32, v[116:119] offset:256
	ds_write_b64 v33, v[120:121] offset:256
	ds_write_b64 v34, v[122:123] offset:256
	ds_write_b64 v34, v[124:125] offset:384
	ds_write_b32 v35, v113 offset:256
	v_add_u32_e32 v28, s19, v32
	v_add_u32_e32 v29, s19, v33
	v_add_u32_e32 v30, s19, v34
	v_add_u32_e32 v31, s19, v35
	global_load_dword v108, v36, s[8:9]
	global_load_dword v109, v36, s[8:9] offset:-2048
	global_load_dword v111, v104, s[8:9] offset:2048
	global_load_dword v110, v37, s[10:11]
	global_load_dword v112, v105, s[10:11]
	global_load_dword v113, v106, s[12:13]
	s_add_u32 s8, s8, 0xc000
	s_addc_u32 s9, s9, 0
	s_add_u32 s10, s10, 0x20000
	s_addc_u32 s11, s11, 0
	s_add_u32 s12, s12, 0x400
	s_addc_u32 s13, s13, 0
	s_waitcnt vmcnt(0)
	v_lshlrev_b32_e32 v116, 16, v108
	v_lshlrev_b32_e32 v117, 16, v109
	v_and_b32_e32 v118, s17, v108
	v_and_b32_e32 v119, s17, v109
	v_lshlrev_b32_e32 v120, 16, v110
	v_and_b32_e32 v121, s17, v110
	v_lshlrev_b32_e32 v122, 16, v111
	v_and_b32_e32 v123, s17, v111
	v_lshlrev_b32_e32 v124, 16, v112
	v_and_b32_e32 v125, s17, v112
	ds_write_b128 v32, v[116:119] offset:16640
	ds_write_b64 v33, v[120:121] offset:16640
	ds_write_b64 v34, v[122:123] offset:16640
	ds_write_b64 v34, v[124:125] offset:16768
	ds_write_b32 v35, v113 offset:16640
	v_add_u32_e32 v28, s20, v32
	v_add_u32_e32 v29, s20, v33
	v_add_u32_e32 v30, s20, v34
	v_add_u32_e32 v31, s20, v35
	v_add_u32_e32 v22, s18, v2
	v_add_u32_e32 v23, s18, v3
	v_mov_b32_e32 v24, s18
	v_add_u32_e32 v25, s19, v2
	v_add_u32_e32 v26, s19, v3
	v_mov_b32_e32 v27, s19
	v_mov_b32_e32 v6, 0
	v_mov_b32_e32 v7, 0
	v_mov_b32_e32 v8, 0
	v_mov_b32_e32 v9, 0
	v_mov_b32_e32 v10, 0
	v_mov_b32_e32 v11, 0
	v_mov_b32_e32 v12, 0
	v_mov_b32_e32 v13, 0
	v_mov_b32_e32 v14, 0
	v_mov_b32_e32 v15, 0
	v_mov_b32_e32 v16, 0
	v_mov_b32_e32 v17, 0
	v_mov_b32_e32 v18, 0
	v_mov_b32_e32 v19, 0
	v_mov_b32_e32 v20, 0
	v_mov_b32_e32 v21, 0
	v_mov_b32_e32 v51, 1.0
	s_mov_b32 s16, 0
	s_waitcnt vmcnt(0) lgkmcnt(0)
	s_barrier
	s_setprio 1
	s_mov_b32 s18, 0x10001
	s_mov_b32 s19, 0x10001
	ds_read_b128 v[56:59], v2 offset:256
	ds_read_b128 v[60:63], v2 offset:512
	ds_read_b128 v[64:67], v2 offset:768
	ds_read_b128 v[68:71], v2 offset:1024
	ds_read_b64 v[72:73], v3 offset:12544
	ds_read_b128 v[76:79], v1 offset:14592

.Lgd2_back0_0:
	v_cvt_pk_bf16_f32 v54, v48, v49
	v_pk_mul_f32 v[46:47], v[44:45], v[52:53] op_sel_hi:[1,0]
	v_pk_fma_f32 v[6:7], v[56:57], v[46:47], v[6:7] op_sel_hi:[0,1,1]
	v_pk_fma_f32 v[8:9], v[58:59], v[46:47], v[8:9] op_sel_hi:[0,1,1]
	v_pk_fma_f32 v[10:11], v[60:61], v[46:47], v[10:11] op_sel_hi:[0,1,1]
	v_pk_fma_f32 v[12:13], v[62:63], v[46:47], v[12:13] op_sel_hi:[0,1,1]
	v_pk_fma_f32 v[14:15], v[64:65], v[46:47], v[14:15] op_sel_hi:[0,1,1]
	v_pk_fma_f32 v[16:17], v[66:67], v[46:47], v[16:17] op_sel_hi:[0,1,1]
	v_pk_fma_f32 v[18:19], v[68:69], v[46:47], v[18:19] op_sel_hi:[0,1,1]
	v_pk_fma_f32 v[20:21], v[70:71], v[46:47], v[20:21] op_sel_hi:[0,1,1]
	s_mov_b64 exec, s[18:19]
	global_store_dword v154, v54, s[14:15] offset:-4096
	s_mov_b64 exec, -1
	s_waitcnt lgkmcnt(5)
	v_pk_mul_f32 v[38:39], v[6:7], v[80:81] op_sel_hi:[1,0]
	v_pk_mul_f32 v[40:41], v[6:7], v[80:81] op_sel:[0,1] op_sel_hi:[1,1]
	v_pk_fma_f32 v[38:39], v[8:9], v[82:83], v[38:39] op_sel_hi:[1,0,1]
	v_pk_fma_f32 v[40:41], v[8:9], v[82:83], v[40:41] op_sel:[0,1,0] op_sel_hi:[1,1,1]
	s_waitcnt lgkmcnt(4)
	v_pk_fma_f32 v[38:39], v[10:11], v[84:85], v[38:39] op_sel_hi:[1,0,1]
	v_pk_fma_f32 v[40:41], v[10:11], v[84:85], v[40:41] op_sel:[0,1,0] op_sel_hi:[1,1,1]
	v_pk_fma_f32 v[38:39], v[12:13], v[86:87], v[38:39] op_sel_hi:[1,0,1]
	v_pk_fma_f32 v[40:41], v[12:13], v[86:87], v[40:41] op_sel:[0,1,0] op_sel_hi:[1,1,1]
	s_waitcnt lgkmcnt(3)
	v_pk_fma_f32 v[38:39], v[14:15], v[88:89], v[38:39] op_sel_hi:[1,0,1]
	v_pk_fma_f32 v[40:41], v[14:15], v[88:89], v[40:41] op_sel:[0,1,0] op_sel_hi:[1,1,1]
	v_pk_fma_f32 v[38:39], v[16:17], v[90:91], v[38:39] op_sel_hi:[1,0,1]
	v_pk_fma_f32 v[40:41], v[16:17], v[90:91], v[40:41] op_sel:[0,1,0] op_sel_hi:[1,1,1]
	s_waitcnt lgkmcnt(2)
	v_pk_fma_f32 v[38:39], v[18:19], v[92:93], v[38:39] op_sel_hi:[1,0,1]
	v_pk_fma_f32 v[40:41], v[18:19], v[92:93], v[40:41] op_sel:[0,1,0] op_sel_hi:[1,1,1]
	v_pk_fma_f32 v[38:39], v[20:21], v[94:95], v[38:39] op_sel_hi:[1,0,1]
	v_pk_fma_f32 v[40:41], v[20:21], v[94:95], v[40:41] op_sel:[0,1,0] op_sel_hi:[1,1,1]
	s_waitcnt lgkmcnt(0)
	v_mul_f32_e32 v51, v100, v50
	v_add_f32_dpp v38, v38, v38 row_ror:8 row_mask:0xf bank_mask:0x3 bound_ctrl:1
	v_add_f32_dpp v39, v39, v39 row_ror:8 row_mask:0xf bank_mask:0x3 bound_ctrl:1
	v_add_f32_dpp v38, v40, v40 row_ror:8 row_mask:0xf bank_mask:0xc bound_ctrl:1
	v_add_f32_dpp v39, v41, v41 row_ror:8 row_mask:0xf bank_mask:0xc bound_ctrl:1
	ds_read_b128 v[56:59], v2 offset:2304
	v_add_f32_dpp v38, v38, v38 row_half_mirror row_mask:0xf bank_mask:0x5 bound_ctrl:1
	v_add_f32_dpp v38, v39, v39 row_half_mirror row_mask:0xf bank_mask:0xa bound_ctrl:1
	ds_read_b128 v[60:63], v2 offset:2560
	ds_read_b128 v[64:67], v2 offset:2816
	v_add_f32_dpp v38, v38, v38 quad_perm:[1,0,3,2] row_mask:0xf bank_mask:0xf bound_ctrl:1
	ds_read_b128 v[68:71], v2 offset:3072
	ds_read_b64 v[72:73], v3 offset:13056
	v_add_f32_dpp v38, v38, v38 quad_perm:[2,3,0,1] row_mask:0xf bank_mask:0xf bound_ctrl:1
	ds_read_b128 v[76:79], v1 offset:14624
	v_cmp_gt_f32_e32 vcc, 0x2b8cbccc, v51
	v_fmac_f32_dpp v96, -v38, v51 row_newbcast:0 row_mask:0xf bank_mask:0xf bound_ctrl:1
	v_fmac_f32_dpp v97, -v38, v51 row_newbcast:4 row_mask:0xf bank_mask:0xf bound_ctrl:1
	v_pk_mul_f32 v[44:45], v[96:97], v[100:101] op_sel:[0,1] op_sel_hi:[1,1]
	v_pk_mul_f32 v[48:49], v[44:45], v[102:103] op_sel_hi:[1,0]
	v_rcp_f32_e32 v52, v51
	s_add_u32 s14, s14, 0x1000
	s_addc_u32 s15, s15, 0
	v_fmac_f32_dpp v48, v38, v51 row_newbcast:8 row_mask:0xf bank_mask:0xf bound_ctrl:1
	v_fmac_f32_dpp v49, v38, v51 row_newbcast:12 row_mask:0xf bank_mask:0xf bound_ctrl:1
	s_cbranch_vccnz .Lgd2_rare0_1
.Lgd2_back0_1:
	v_cvt_pk_bf16_f32 v54, v48, v49
	v_pk_mul_f32 v[46:47], v[44:45], v[52:53] op_sel_hi:[1,0]
	v_pk_fma_f32 v[6:7], v[80:81], v[46:47], v[6:7] op_sel_hi:[0,1,1]
	v_pk_fma_f32 v[8:9], v[82:83], v[46:47], v[8:9] op_sel_hi:[0,1,1]
	v_pk_fma_f32 v[10:11], v[84:85], v[46:47], v[10:11] op_sel_hi:[0,1,1]
	v_pk_fma_f32 v[12:13], v[86:87], v[46:47], v[12:13] op_sel_hi:[0,1,1]
	v_pk_fma_f32 v[14:15], v[88:89], v[46:47], v[14:15] op_sel_hi:[0,1,1]
	v_pk_fma_f32 v[16:17], v[90:91], v[46:47], v[16:17] op_sel_hi:[0,1,1]
	v_pk_fma_f32 v[18:19], v[92:93], v[46:47], v[18:19] op_sel_hi:[0,1,1]
	v_pk_fma_f32 v[20:21], v[94:95], v[46:47], v[20:21] op_sel_hi:[0,1,1]
	s_mov_b64 exec, s[18:19]
	global_store_dword v154, v54, s[14:15] offset:-4096
	s_mov_b64 exec, -1
	s_waitcnt lgkmcnt(5)
	v_pk_mul_f32 v[38:39], v[6:7], v[56:57] op_sel_hi:[1,0]
	v_pk_mul_f32 v[40:41], v[6:7], v[56:57] op_sel:[0,1] op_sel_hi:[1,1]
	v_pk_fma_f32 v[38:39], v[8:9], v[58:59], v[38:39] op_sel_hi:[1,0,1]
	v_pk_fma_f32 v[40:41], v[8:9], v[58:59], v[40:41] op_sel:[0,1,0] op_sel_hi:[1,1,1]
	s_waitcnt lgkmcnt(4)
	v_pk_fma_f32 v[38:39], v[10:11], v[60:61], v[38:39] op_sel_hi:[1,0,1]
	v_pk_fma_f32 v[40:41], v[10:11], v[60:61], v[40:41] op_sel:[0,1,0] op_sel_hi:[1,1,1]
	v_pk_fma_f32 v[38:39], v[12:13], v[62:63], v[38:39] op_sel_hi:[1,0,1]
	v_pk_fma_f32 v[40:41], v[12:13], v[62:63], v[40:41] op_sel:[0,1,0] op_sel_hi:[1,1,1]
	s_waitcnt lgkmcnt(3)
	v_pk_fma_f32 v[38:39], v[14:15], v[64:65], v[38:39] op_sel_hi:[1,0,1]
	v_pk_fma_f32 v[40:41], v[14:15], v[64:65], v[40:41] op_sel:[0,1,0] op_sel_hi:[1,1,1]
	v_pk_fma_f32 v[38:39], v[16:17], v[66:67], v[38:39] op_sel_hi:[1,0,1]
	v_pk_fma_f32 v[40:41], v[16:17], v[66:67], v[40:41] op_sel:[0,1,0] op_sel_hi:[1,1,1]
	s_waitcnt lgkmcnt(2)
	v_pk_fma_f32 v[38:39], v[18:19], v[68:69], v[38:39] op_sel_hi:[1,0,1]
	v_pk_fma_f32 v[40:41], v[18:19], v[68:69], v[40:41] op_sel:[0,1,0] op_sel_hi:[1,1,1]
	v_pk_fma_f32 v[38:39], v[20:21], v[70:71], v[38:39] op_sel_hi:[1,0,1]
	v_pk_fma_f32 v[40:41], v[20:21], v[70:71], v[40:41] op_sel:[0,1,0] op_sel_hi:[1,1,1]
	s_waitcnt lgkmcnt(0)
	v_mul_f32_e32 v50, v76, v51
	v_add_f32_dpp v38, v38, v38 row_ror:8 row_mask:0xf bank_mask:0x3 bound_ctrl:1
	v_add_f32_dpp v39, v39, v39 row_ror:8 row_mask:0xf bank_mask:0x3 bound_ctrl:1
	v_add_f32_dpp v38, v40, v40 row_ror:8 row_mask:0xf bank_mask:0xc bound_ctrl:1
	v_add_f32_dpp v39, v41, v41 row_ror:8 row_mask:0xf bank_mask:0xc bound_ctrl:1
	ds_read_b128 v[80:83], v2 offset:3328
	v_add_f32_dpp v38, v38, v38 row_half_mirror row_mask:0xf bank_mask:0x5 bound_ctrl:1
	v_add_f32_dpp v38, v39, v39 row_half_mirror row_mask:0xf bank_mask:0xa bound_ctrl:1
	ds_read_b128 v[84:87], v2 offset:3584
	ds_read_b128 v[88:91], v2 offset:3840
	v_add_f32_dpp v38, v38, v38 quad_perm:[1,0,3,2] row_mask:0xf bank_mask:0xf bound_ctrl:1
	ds_read_b128 v[92:95], v2 offset:4096
	ds_read_b64 v[96:97], v3 offset:13312
	v_add_f32_dpp v38, v38, v38 quad_perm:[2,3,0,1] row_mask:0xf bank_mask:0xf bound_ctrl:1
	ds_read_b128 v[100:103], v1 offset:14640
	v_cmp_gt_f32_e32 vcc, 0x2b8cbccc, v50
	v_fmac_f32_dpp v72, -v38, v50 row_newbcast:0 row_mask:0xf bank_mask:0xf bound_ctrl:1
	v_fmac_f32_dpp v73, -v38, v50 row_newbcast:4 row_mask:0xf bank_mask:0xf bound_ctrl:1
	v_pk_mul_f32 v[44:45], v[72:73], v[76:77] op_sel:[0,1] op_sel_hi:[1,1]
	v_pk_mul_f32 v[48:49], v[44:45], v[78:79] op_sel_hi:[1,0]
	v_rcp_f32_e32 v52, v50
	s_add_u32 s14, s14, 0x1000
	s_addc_u32 s15, s15, 0
	v_fmac_f32_dpp v48, v38, v50 row_newbcast:8 row_mask:0xf bank_mask:0xf bound_ctrl:1
	v_fmac_f32_dpp v49, v38, v50 row_newbcast:12 row_mask:0xf bank_mask:0xf bound_ctrl:1
	s_cbranch_vccnz .Lgd2_rare0_2
.Lgd2_back0_2:
	v_cvt_pk_bf16_f32 v54, v48, v49
	v_pk_mul_f32 v[46:47], v[44:45], v[52:53] op_sel_hi:[1,0]
	v_pk_fma_f32 v[6:7], v[56:57], v[46:47], v[6:7] op_sel_hi:[0,1,1]
	v_pk_fma_f32 v[8:9], v[58:59], v[46:47], v[8:9] op_sel_hi:[0,1,1]
	v_pk_fma_f32 v[10:11], v[60:61], v[46:47], v[10:11] op_sel_hi:[0,1,1]
	v_pk_fma_f32 v[12:13], v[62:63], v[46:47], v[12:13] op_sel_hi:[0,1,1]
	v_pk_fma_f32 v[14:15], v[64:65], v[46:47], v[14:15] op_sel_hi:[0,1,1]
	v_pk_fma_f32 v[16:17], v[66:67], v[46:47], v[16:17] op_sel_hi:[0,1,1]
	v_pk_fma_f32 v[18:19], v[68:69], v[46:47], v[18:19] op_sel_hi:[0,1,1]
	v_pk_fma_f32 v[20:21], v[70:71], v[46:47], v[20:21] op_sel_hi:[0,1,1]
	s_mov_b64 exec, s[18:19]
	global_store_dword v154, v54, s[14:15] offset:-4096
	s_mov_b64 exec, -1
	s_waitcnt lgkmcnt(5)
	v_pk_mul_f32 v[38:39], v[6:7], v[80:81] op_sel_hi:[1,0]
	v_pk_mul_f32 v[40:41], v[6:7], v[80:81] op_sel:[0,1] op_sel_hi:[1,1]
	v_pk_fma_f32 v[38:39], v[8:9], v[82:83], v[38:39] op_sel_hi:[1,0,1]
	v_pk_fma_f32 v[40:41], v[8:9], v[82:83], v[40:41] op_sel:[0,1,0] op_sel_hi:[1,1,1]
	s_waitcnt lgkmcnt(4)
	v_pk_fma_f32 v[38:39], v[10:11], v[84:85], v[38:39] op_sel_hi:[1,0,1]
	v_pk_fma_f32 v[40:41], v[10:11], v[84:85], v[40:41] op_sel:[0,1,0] op_sel_hi:[1,1,1]
	v_pk_fma_f32 v[38:39], v[12:13], v[86:87], v[38:39] op_sel_hi:[1,0,1]
	v_pk_fma_f32 v[40:41], v[12:13], v[86:87], v[40:41] op_sel:[0,1,0] op_sel_hi:[1,1,1]
	s_waitcnt lgkmcnt(3)
	v_pk_fma_f32 v[38:39], v[14:15], v[88:89], v[38:39] op_sel_hi:[1,0,1]
	v_pk_fma_f32 v[40:41], v[14:15], v[88:89], v[40:41] op_sel:[0,1,0] op_sel_hi:[1,1,1]
	v_pk_fma_f32 v[38:39], v[16:17], v[90:91], v[38:39] op_sel_hi:[1,0,1]
	v_pk_fma_f32 v[40:41], v[16:17], v[90:91], v[40:41] op_sel:[0,1,0] op_sel_hi:[1,1,1]
	s_waitcnt lgkmcnt(2)
	v_pk_fma_f32 v[38:39], v[18:19], v[92:93], v[38:39] op_sel_hi:[1,0,1]
	v_pk_fma_f32 v[40:41], v[18:19], v[92:93], v[40:41] op_sel:[0,1,0] op_sel_hi:[1,1,1]
	v_pk_fma_f32 v[38:39], v[20:21], v[94:95], v[38:39] op_sel_hi:[1,0,1]
	v_pk_fma_f32 v[40:41], v[20:21], v[94:95], v[40:41] op_sel:[0,1,0] op_sel_hi:[1,1,1]
	s_waitcnt lgkmcnt(0)
	v_mul_f32_e32 v51, v100, v50
	v_add_f32_dpp v38, v38, v38 row_ror:8 row_mask:0xf bank_mask:0x3 bound_ctrl:1
	v_add_f32_dpp v39, v39, v39 row_ror:8 row_mask:0xf bank_mask:0x3 bound_ctrl:1
	v_add_f32_dpp v38, v40, v40 row_ror:8 row_mask:0xf bank_mask:0xc bound_ctrl:1
	v_add_f32_dpp v39, v41, v41 row_ror:8 row_mask:0xf bank_mask:0xc bound_ctrl:1
	ds_read_b128 v[56:59], v2 offset:4352
	v_add_f32_dpp v38, v38, v38 row_half_mirror row_mask:0xf bank_mask:0x5 bound_ctrl:1
	v_add_f32_dpp v38, v39, v39 row_half_mirror row_mask:0xf bank_mask:0xa bound_ctrl:1
	ds_read_b128 v[60:63], v2 offset:4608
	ds_read_b128 v[64:67], v2 offset:4864
	v_add_f32_dpp v38, v38, v38 quad_perm:[1,0,3,2] row_mask:0xf bank_mask:0xf bound_ctrl:1
	ds_read_b128 v[68:71], v2 offset:5120
	ds_read_b64 v[72:73], v3 offset:13568
	v_add_f32_dpp v38, v38, v38 quad_perm:[2,3,0,1] row_mask:0xf bank_mask:0xf bound_ctrl:1
	ds_read_b128 v[76:79], v1 offset:14656
	v_cmp_gt_f32_e32 vcc, 0x2b8cbccc, v51
	v_fmac_f32_dpp v96, -v38, v51 row_newbcast:0 row_mask:0xf bank_mask:0xf bound_ctrl:1
	v_fmac_f32_dpp v97, -v38, v51 row_newbcast:4 row_mask:0xf bank_mask:0xf bound_ctrl:1
	v_pk_mul_f32 v[44:45], v[96:97], v[100:101] op_sel:[0,1] op_sel_hi:[1,1]
	v_pk_mul_f32 v[48:49], v[44:45], v[102:103] op_sel_hi:[1,0]
	v_rcp_f32_e32 v52, v51
	s_add_u32 s14, s14, 0x1000
	s_addc_u32 s15, s15, 0
	v_fmac_f32_dpp v48, v38, v51 row_newbcast:8 row_mask:0xf bank_mask:0xf bound_ctrl:1
	v_fmac_f32_dpp v49, v38, v51 row_newbcast:12 row_mask:0xf bank_mask:0xf bound_ctrl:1
	s_cbranch_vccnz .Lgd2_rare0_3
.Lgd2_back0_3:
	v_cvt_pk_bf16_f32 v54, v48, v49
	v_pk_mul_f32 v[46:47], v[44:45], v[52:53] op_sel_hi:[1,0]
	v_pk_fma_f32 v[6:7], v[80:81], v[46:47], v[6:7] op_sel_hi:[0,1,1]
	v_pk_fma_f32 v[8:9], v[82:83], v[46:47], v[8:9] op_sel_hi:[0,1,1]
	v_pk_fma_f32 v[10:11], v[84:85], v[46:47], v[10:11] op_sel_hi:[0,1,1]
	v_pk_fma_f32 v[12:13], v[86:87], v[46:47], v[12:13] op_sel_hi:[0,1,1]
	v_pk_fma_f32 v[14:15], v[88:89], v[46:47], v[14:15] op_sel_hi:[0,1,1]
	v_pk_fma_f32 v[16:17], v[90:91], v[46:47], v[16:17] op_sel_hi:[0,1,1]
	v_pk_fma_f32 v[18:19], v[92:93], v[46:47], v[18:19] op_sel_hi:[0,1,1]
	v_pk_fma_f32 v[20:21], v[94:95], v[46:47], v[20:21] op_sel_hi:[0,1,1]
	s_mov_b64 exec, s[18:19]
	global_store_dword v154, v54, s[14:15] offset:-4096
	s_mov_b64 exec, -1
	s_waitcnt lgkmcnt(5)
	v_pk_mul_f32 v[38:39], v[6:7], v[56:57] op_sel_hi:[1,0]
	v_pk_mul_f32 v[40:41], v[6:7], v[56:57] op_sel:[0,1] op_sel_hi:[1,1]
	v_pk_fma_f32 v[38:39], v[8:9], v[58:59], v[38:39] op_sel_hi:[1,0,1]
	v_pk_fma_f32 v[40:41], v[8:9], v[58:59], v[40:41] op_sel:[0,1,0] op_sel_hi:[1,1,1]
	s_waitcnt lgkmcnt(4)
	v_pk_fma_f32 v[38:39], v[10:11], v[60:61], v[38:39] op_sel_hi:[1,0,1]
	v_pk_fma_f32 v[40:41], v[10:11], v[60:61], v[40:41] op_sel:[0,1,0] op_sel_hi:[1,1,1]
	v_pk_fma_f32 v[38:39], v[12:13], v[62:63], v[38:39] op_sel_hi:[1,0,1]
	v_pk_fma_f32 v[40:41], v[12:13], v[62:63], v[40:41] op_sel:[0,1,0] op_sel_hi:[1,1,1]
	s_waitcnt lgkmcnt(3)
	v_pk_fma_f32 v[38:39], v[14:15], v[64:65], v[38:39] op_sel_hi:[1,0,1]
	v_pk_fma_f32 v[40:41], v[14:15], v[64:65], v[40:41] op_sel:[0,1,0] op_sel_hi:[1,1,1]
	v_pk_fma_f32 v[38:39], v[16:17], v[66:67], v[38:39] op_sel_hi:[1,0,1]
	v_pk_fma_f32 v[40:41], v[16:17], v[66:67], v[40:41] op_sel:[0,1,0] op_sel_hi:[1,1,1]
	s_waitcnt lgkmcnt(2)
	v_pk_fma_f32 v[38:39], v[18:19], v[68:69], v[38:39] op_sel_hi:[1,0,1]
	v_pk_fma_f32 v[40:41], v[18:19], v[68:69], v[40:41] op_sel:[0,1,0] op_sel_hi:[1,1,1]
	v_pk_fma_f32 v[38:39], v[20:21], v[70:71], v[38:39] op_sel_hi:[1,0,1]
	v_pk_fma_f32 v[40:41], v[20:21], v[70:71], v[40:41] op_sel:[0,1,0] op_sel_hi:[1,1,1]
	s_waitcnt lgkmcnt(0)
	v_mul_f32_e32 v50, v76, v51
	v_add_f32_dpp v38, v38, v38 row_ror:8 row_mask:0xf bank_mask:0x3 bound_ctrl:1
	v_add_f32_dpp v39, v39, v39 row_ror:8 row_mask:0xf bank_mask:0x3 bound_ctrl:1
	v_add_f32_dpp v38, v40, v40 row_ror:8 row_mask:0xf bank_mask:0xc bound_ctrl:1
	v_add_f32_dpp v39, v41, v41 row_ror:8 row_mask:0xf bank_mask:0xc bound_ctrl:1
	ds_read_b128 v[80:83], v2 offset:5376
	v_add_f32_dpp v38, v38, v38 row_half_mirror row_mask:0xf bank_mask:0x5 bound_ctrl:1
	v_add_f32_dpp v38, v39, v39 row_half_mirror row_mask:0xf bank_mask:0xa bound_ctrl:1
	ds_read_b128 v[84:87], v2 offset:5632
	ds_read_b128 v[88:91], v2 offset:5888
	v_add_f32_dpp v38, v38, v38 quad_perm:[1,0,3,2] row_mask:0xf bank_mask:0xf bound_ctrl:1
	ds_read_b128 v[92:95], v2 offset:6144
	ds_read_b64 v[96:97], v3 offset:13824
	v_add_f32_dpp v38, v38, v38 quad_perm:[2,3,0,1] row_mask:0xf bank_mask:0xf bound_ctrl:1
	ds_read_b128 v[100:103], v1 offset:14672
	v_cmp_gt_f32_e32 vcc, 0x2b8cbccc, v50
	v_fmac_f32_dpp v72, -v38, v50 row_newbcast:0 row_mask:0xf bank_mask:0xf bound_ctrl:1
	v_fmac_f32_dpp v73, -v38, v50 row_newbcast:4 row_mask:0xf bank_mask:0xf bound_ctrl:1
	v_pk_mul_f32 v[44:45], v[72:73], v[76:77] op_sel:[0,1] op_sel_hi:[1,1]
	v_pk_mul_f32 v[48:49], v[44:45], v[78:79] op_sel_hi:[1,0]
	v_rcp_f32_e32 v52, v50
	s_add_u32 s14, s14, 0x1000
	s_addc_u32 s15, s15, 0
	v_fmac_f32_dpp v48, v38, v50 row_newbcast:8 row_mask:0xf bank_mask:0xf bound_ctrl:1
	v_fmac_f32_dpp v49, v38, v50 row_newbcast:12 row_mask:0xf bank_mask:0xf bound_ctrl:1
	s_cbranch_vccnz .Lgd2_rare0_4
.Lgd2_back0_4:
	v_cvt_pk_bf16_f32 v54, v48, v49
	v_pk_mul_f32 v[46:47], v[44:45], v[52:53] op_sel_hi:[1,0]
	v_pk_fma_f32 v[6:7], v[56:57], v[46:47], v[6:7] op_sel_hi:[0,1,1]
	v_pk_fma_f32 v[8:9], v[58:59], v[46:47], v[8:9] op_sel_hi:[0,1,1]
	v_pk_fma_f32 v[10:11], v[60:61], v[46:47], v[10:11] op_sel_hi:[0,1,1]
	v_pk_fma_f32 v[12:13], v[62:63], v[46:47], v[12:13] op_sel_hi:[0,1,1]
	v_pk_fma_f32 v[14:15], v[64:65], v[46:47], v[14:15] op_sel_hi:[0,1,1]
	v_pk_fma_f32 v[16:17], v[66:67], v[46:47], v[16:17] op_sel_hi:[0,1,1]
	v_pk_fma_f32 v[18:19], v[68:69], v[46:47], v[18:19] op_sel_hi:[0,1,1]
	v_pk_fma_f32 v[20:21], v[70:71], v[46:47], v[20:21] op_sel_hi:[0,1,1]
	s_mov_b64 exec, s[18:19]
	global_store_dword v154, v54, s[14:15] offset:-4096
	s_mov_b64 exec, -1
	s_waitcnt lgkmcnt(5)
	v_pk_mul_f32 v[38:39], v[6:7], v[80:81] op_sel_hi:[1,0]
	v_pk_mul_f32 v[40:41], v[6:7], v[80:81] op_sel:[0,1] op_sel_hi:[1,1]
	v_pk_fma_f32 v[38:39], v[8:9], v[82:83], v[38:39] op_sel_hi:[1,0,1]
	v_pk_fma_f32 v[40:41], v[8:9], v[82:83], v[40:41] op_sel:[0,1,0] op_sel_hi:[1,1,1]
	s_waitcnt lgkmcnt(4)
	v_pk_fma_f32 v[38:39], v[10:11], v[84:85], v[38:39] op_sel_hi:[1,0,1]
	v_pk_fma_f32 v[40:41], v[10:11], v[84:85], v[40:41] op_sel:[0,1,0] op_sel_hi:[1,1,1]
	v_pk_fma_f32 v[38:39], v[12:13], v[86:87], v[38:39] op_sel_hi:[1,0,1]
	v_pk_fma_f32 v[40:41], v[12:13], v[86:87], v[40:41] op_sel:[0,1,0] op_sel_hi:[1,1,1]
	s_waitcnt lgkmcnt(3)
	v_pk_fma_f32 v[38:39], v[14:15], v[88:89], v[38:39] op_sel_hi:[1,0,1]
	v_pk_fma_f32 v[40:41], v[14:15], v[88:89], v[40:41] op_sel:[0,1,0] op_sel_hi:[1,1,1]
	v_pk_fma_f32 v[38:39], v[16:17], v[90:91], v[38:39] op_sel_hi:[1,0,1]
	v_pk_fma_f32 v[40:41], v[16:17], v[90:91], v[40:41] op_sel:[0,1,0] op_sel_hi:[1,1,1]
	s_waitcnt lgkmcnt(2)
	v_pk_fma_f32 v[38:39], v[18:19], v[92:93], v[38:39] op_sel_hi:[1,0,1]
	v_pk_fma_f32 v[40:41], v[18:19], v[92:93], v[40:41] op_sel:[0,1,0] op_sel_hi:[1,1,1]
	v_pk_fma_f32 v[38:39], v[20:21], v[94:95], v[38:39] op_sel_hi:[1,0,1]
	v_pk_fma_f32 v[40:41], v[20:21], v[94:95], v[40:41] op_sel:[0,1,0] op_sel_hi:[1,1,1]
	s_waitcnt lgkmcnt(0)
	v_mul_f32_e32 v51, v100, v50
	v_add_f32_dpp v38, v38, v38 row_ror:8 row_mask:0xf bank_mask:0x3 bound_ctrl:1
	v_add_f32_dpp v39, v39, v39 row_ror:8 row_mask:0xf bank_mask:0x3 bound_ctrl:1
	v_add_f32_dpp v38, v40, v40 row_ror:8 row_mask:0xf bank_mask:0xc bound_ctrl:1
	v_add_f32_dpp v39, v41, v41 row_ror:8 row_mask:0xf bank_mask:0xc bound_ctrl:1
	ds_read_b128 v[56:59], v2 offset:6400
	v_add_f32_dpp v38, v38, v38 row_half_mirror row_mask:0xf bank_mask:0x5 bound_ctrl:1
	v_add_f32_dpp v38, v39, v39 row_half_mirror row_mask:0xf bank_mask:0xa bound_ctrl:1
	ds_read_b128 v[60:63], v2 offset:6656
	ds_read_b128 v[64:67], v2 offset:6912
	v_add_f32_dpp v38, v38, v38 quad_perm:[1,0,3,2] row_mask:0xf bank_mask:0xf bound_ctrl:1
	ds_read_b128 v[68:71], v2 offset:7168
	ds_read_b64 v[72:73], v3 offset:14080
	v_add_f32_dpp v38, v38, v38 quad_perm:[2,3,0,1] row_mask:0xf bank_mask:0xf bound_ctrl:1
	ds_read_b128 v[76:79], v1 offset:14688
	v_cmp_gt_f32_e32 vcc, 0x2b8cbccc, v51
	v_fmac_f32_dpp v96, -v38, v51 row_newbcast:0 row_mask:0xf bank_mask:0xf bound_ctrl:1
	v_fmac_f32_dpp v97, -v38, v51 row_newbcast:4 row_mask:0xf bank_mask:0xf bound_ctrl:1
	v_pk_mul_f32 v[44:45], v[96:97], v[100:101] op_sel:[0,1] op_sel_hi:[1,1]
	v_pk_mul_f32 v[48:49], v[44:45], v[102:103] op_sel_hi:[1,0]
	v_rcp_f32_e32 v52, v51
	s_add_u32 s14, s14, 0x1000
	s_addc_u32 s15, s15, 0
	v_fmac_f32_dpp v48, v38, v51 row_newbcast:8 row_mask:0xf bank_mask:0xf bound_ctrl:1
	v_fmac_f32_dpp v49, v38, v51 row_newbcast:12 row_mask:0xf bank_mask:0xf bound_ctrl:1
	s_cbranch_vccnz .Lgd2_rare0_5
.Lgd2_back0_5:
	v_cvt_pk_bf16_f32 v54, v48, v49
	v_pk_mul_f32 v[46:47], v[44:45], v[52:53] op_sel_hi:[1,0]
	v_pk_fma_f32 v[6:7], v[80:81], v[46:47], v[6:7] op_sel_hi:[0,1,1]
	v_pk_fma_f32 v[8:9], v[82:83], v[46:47], v[8:9] op_sel_hi:[0,1,1]
	v_pk_fma_f32 v[10:11], v[84:85], v[46:47], v[10:11] op_sel_hi:[0,1,1]
	v_pk_fma_f32 v[12:13], v[86:87], v[46:47], v[12:13] op_sel_hi:[0,1,1]
	v_pk_fma_f32 v[14:15], v[88:89], v[46:47], v[14:15] op_sel_hi:[0,1,1]
	v_pk_fma_f32 v[16:17], v[90:91], v[46:47], v[16:17] op_sel_hi:[0,1,1]
	v_pk_fma_f32 v[18:19], v[92:93], v[46:47], v[18:19] op_sel_hi:[0,1,1]
	v_pk_fma_f32 v[20:21], v[94:95], v[46:47], v[20:21] op_sel_hi:[0,1,1]
	s_mov_b64 exec, s[18:19]
	global_store_dword v154, v54, s[14:15] offset:-4096
	s_mov_b64 exec, -1
	s_waitcnt lgkmcnt(5)
	v_pk_mul_f32 v[38:39], v[6:7], v[56:57] op_sel_hi:[1,0]
	v_pk_mul_f32 v[40:41], v[6:7], v[56:57] op_sel:[0,1] op_sel_hi:[1,1]
	v_pk_fma_f32 v[38:39], v[8:9], v[58:59], v[38:39] op_sel_hi:[1,0,1]
	v_pk_fma_f32 v[40:41], v[8:9], v[58:59], v[40:41] op_sel:[0,1,0] op_sel_hi:[1,1,1]
	s_waitcnt lgkmcnt(4)
	v_pk_fma_f32 v[38:39], v[10:11], v[60:61], v[38:39] op_sel_hi:[1,0,1]
	v_pk_fma_f32 v[40:41], v[10:11], v[60:61], v[40:41] op_sel:[0,1,0] op_sel_hi:[1,1,1]
	v_pk_fma_f32 v[38:39], v[12:13], v[62:63], v[38:39] op_sel_hi:[1,0,1]
	v_pk_fma_f32 v[40:41], v[12:13], v[62:63], v[40:41] op_sel:[0,1,0] op_sel_hi:[1,1,1]
	s_waitcnt lgkmcnt(3)
	v_pk_fma_f32 v[38:39], v[14:15], v[64:65], v[38:39] op_sel_hi:[1,0,1]
	v_pk_fma_f32 v[40:41], v[14:15], v[64:65], v[40:41] op_sel:[0,1,0] op_sel_hi:[1,1,1]
	v_pk_fma_f32 v[38:39], v[16:17], v[66:67], v[38:39] op_sel_hi:[1,0,1]
	v_pk_fma_f32 v[40:41], v[16:17], v[66:67], v[40:41] op_sel:[0,1,0] op_sel_hi:[1,1,1]
	s_waitcnt lgkmcnt(2)
	v_pk_fma_f32 v[38:39], v[18:19], v[68:69], v[38:39] op_sel_hi:[1,0,1]
	v_pk_fma_f32 v[40:41], v[18:19], v[68:69], v[40:41] op_sel:[0,1,0] op_sel_hi:[1,1,1]
	v_pk_fma_f32 v[38:39], v[20:21], v[70:71], v[38:39] op_sel_hi:[1,0,1]
	v_pk_fma_f32 v[40:41], v[20:21], v[70:71], v[40:41] op_sel:[0,1,0] op_sel_hi:[1,1,1]
	s_waitcnt lgkmcnt(0)
	v_mul_f32_e32 v50, v76, v51
	v_add_f32_dpp v38, v38, v38 row_ror:8 row_mask:0xf bank_mask:0x3 bound_ctrl:1
	v_add_f32_dpp v39, v39, v39 row_ror:8 row_mask:0xf bank_mask:0x3 bound_ctrl:1
	v_add_f32_dpp v38, v40, v40 row_ror:8 row_mask:0xf bank_mask:0xc bound_ctrl:1
	v_add_f32_dpp v39, v41, v41 row_ror:8 row_mask:0xf bank_mask:0xc bound_ctrl:1
	ds_read_b128 v[80:83], v2 offset:7424
	v_add_f32_dpp v38, v38, v38 row_half_mirror row_mask:0xf bank_mask:0x5 bound_ctrl:1
	v_add_f32_dpp v38, v39, v39 row_half_mirror row_mask:0xf bank_mask:0xa bound_ctrl:1
	ds_read_b128 v[84:87], v2 offset:7680
	ds_read_b128 v[88:91], v2 offset:7936
	v_add_f32_dpp v38, v38, v38 quad_perm:[1,0,3,2] row_mask:0xf bank_mask:0xf bound_ctrl:1
	ds_read_b128 v[92:95], v2 offset:8192
	ds_read_b64 v[96:97], v3 offset:14336
	v_add_f32_dpp v38, v38, v38 quad_perm:[2,3,0,1] row_mask:0xf bank_mask:0xf bound_ctrl:1
	ds_read_b128 v[100:103], v1 offset:14704
	v_cmp_gt_f32_e32 vcc, 0x2b8cbccc, v50
	v_fmac_f32_dpp v72, -v38, v50 row_newbcast:0 row_mask:0xf bank_mask:0xf bound_ctrl:1
	v_fmac_f32_dpp v73, -v38, v50 row_newbcast:4 row_mask:0xf bank_mask:0xf bound_ctrl:1
	v_pk_mul_f32 v[44:45], v[72:73], v[76:77] op_sel:[0,1] op_sel_hi:[1,1]
	v_pk_mul_f32 v[48:49], v[44:45], v[78:79] op_sel_hi:[1,0]
	v_rcp_f32_e32 v52, v50
	s_add_u32 s14, s14, 0x1000
	s_addc_u32 s15, s15, 0
	v_fmac_f32_dpp v48, v38, v50 row_newbcast:8 row_mask:0xf bank_mask:0xf bound_ctrl:1
	v_fmac_f32_dpp v49, v38, v50 row_newbcast:12 row_mask:0xf bank_mask:0xf bound_ctrl:1
	s_cbranch_vccnz .Lgd2_rare0_6
.Lgd2_back0_6:
	v_cvt_pk_bf16_f32 v54, v48, v49
	v_pk_mul_f32 v[46:47], v[44:45], v[52:53] op_sel_hi:[1,0]
	v_pk_fma_f32 v[6:7], v[56:57], v[46:47], v[6:7] op_sel_hi:[0,1,1]
	v_pk_fma_f32 v[8:9], v[58:59], v[46:47], v[8:9] op_sel_hi:[0,1,1]
	v_pk_fma_f32 v[10:11], v[60:61], v[46:47], v[10:11] op_sel_hi:[0,1,1]
	v_pk_fma_f32 v[12:13], v[62:63], v[46:47], v[12:13] op_sel_hi:[0,1,1]
	v_pk_fma_f32 v[14:15], v[64:65], v[46:47], v[14:15] op_sel_hi:[0,1,1]
	v_pk_fma_f32 v[16:17], v[66:67], v[46:47], v[16:17] op_sel_hi:[0,1,1]
	v_pk_fma_f32 v[18:19], v[68:69], v[46:47], v[18:19] op_sel_hi:[0,1,1]
	v_pk_fma_f32 v[20:21], v[70:71], v[46:47], v[20:21] op_sel_hi:[0,1,1]
	s_mov_b64 exec, s[18:19]
	global_store_dword v154, v54, s[14:15] offset:-4096
	s_mov_b64 exec, -1
	s_waitcnt lgkmcnt(5)
	v_pk_mul_f32 v[38:39], v[6:7], v[80:81] op_sel_hi:[1,0]
	v_pk_mul_f32 v[40:41], v[6:7], v[80:81] op_sel:[0,1] op_sel_hi:[1,1]
	v_pk_fma_f32 v[38:39], v[8:9], v[82:83], v[38:39] op_sel_hi:[1,0,1]
	v_pk_fma_f32 v[40:41], v[8:9], v[82:83], v[40:41] op_sel:[0,1,0] op_sel_hi:[1,1,1]
	s_waitcnt lgkmcnt(4)
	v_pk_fma_f32 v[38:39], v[10:11], v[84:85], v[38:39] op_sel_hi:[1,0,1]
	v_pk_fma_f32 v[40:41], v[10:11], v[84:85], v[40:41] op_sel:[0,1,0] op_sel_hi:[1,1,1]
	v_pk_fma_f32 v[38:39], v[12:13], v[86:87], v[38:39] op_sel_hi:[1,0,1]
	v_pk_fma_f32 v[40:41], v[12:13], v[86:87], v[40:41] op_sel:[0,1,0] op_sel_hi:[1,1,1]
	s_waitcnt lgkmcnt(3)
	v_pk_fma_f32 v[38:39], v[14:15], v[88:89], v[38:39] op_sel_hi:[1,0,1]
	v_pk_fma_f32 v[40:41], v[14:15], v[88:89], v[40:41] op_sel:[0,1,0] op_sel_hi:[1,1,1]
	v_pk_fma_f32 v[38:39], v[16:17], v[90:91], v[38:39] op_sel_hi:[1,0,1]
	v_pk_fma_f32 v[40:41], v[16:17], v[90:91], v[40:41] op_sel:[0,1,0] op_sel_hi:[1,1,1]
	s_waitcnt lgkmcnt(2)
	v_pk_fma_f32 v[38:39], v[18:19], v[92:93], v[38:39] op_sel_hi:[1,0,1]
	v_pk_fma_f32 v[40:41], v[18:19], v[92:93], v[40:41] op_sel:[0,1,0] op_sel_hi:[1,1,1]
	v_pk_fma_f32 v[38:39], v[20:21], v[94:95], v[38:39] op_sel_hi:[1,0,1]
	v_pk_fma_f32 v[40:41], v[20:21], v[94:95], v[40:41] op_sel:[0,1,0] op_sel_hi:[1,1,1]
	s_waitcnt lgkmcnt(0)
	v_mul_f32_e32 v51, v100, v50
	v_add_f32_dpp v38, v38, v38 row_ror:8 row_mask:0xf bank_mask:0x3 bound_ctrl:1
	v_add_f32_dpp v39, v39, v39 row_ror:8 row_mask:0xf bank_mask:0x3 bound_ctrl:1
	v_add_f32_dpp v38, v40, v40 row_ror:8 row_mask:0xf bank_mask:0xc bound_ctrl:1
	v_add_f32_dpp v39, v41, v41 row_ror:8 row_mask:0xf bank_mask:0xc bound_ctrl:1
	ds_read_b128 v[56:59], v2 offset:16640
	v_add_f32_dpp v38, v38, v38 row_half_mirror row_mask:0xf bank_mask:0x5 bound_ctrl:1
	v_add_f32_dpp v38, v39, v39 row_half_mirror row_mask:0xf bank_mask:0xa bound_ctrl:1
	ds_read_b128 v[60:63], v2 offset:16896
	ds_read_b128 v[64:67], v2 offset:17152
	v_add_f32_dpp v38, v38, v38 quad_perm:[1,0,3,2] row_mask:0xf bank_mask:0xf bound_ctrl:1
	ds_read_b128 v[68:71], v2 offset:17408
	ds_read_b64 v[72:73], v3 offset:28928
	v_add_f32_dpp v38, v38, v38 quad_perm:[2,3,0,1] row_mask:0xf bank_mask:0xf bound_ctrl:1
	ds_read_b128 v[76:79], v1 offset:30976
	v_cmp_gt_f32_e32 vcc, 0x2b8cbccc, v51
	v_fmac_f32_dpp v96, -v38, v51 row_newbcast:0 row_mask:0xf bank_mask:0xf bound_ctrl:1
	v_fmac_f32_dpp v97, -v38, v51 row_newbcast:4 row_mask:0xf bank_mask:0xf bound_ctrl:1
	v_pk_mul_f32 v[44:45], v[96:97], v[100:101] op_sel:[0,1] op_sel_hi:[1,1]
	v_pk_mul_f32 v[48:49], v[44:45], v[102:103] op_sel_hi:[1,0]
	v_rcp_f32_e32 v52, v51
	s_add_u32 s14, s14, 0x1000
	s_addc_u32 s15, s15, 0
	v_fmac_f32_dpp v48, v38, v51 row_newbcast:8 row_mask:0xf bank_mask:0xf bound_ctrl:1
	v_fmac_f32_dpp v49, v38, v51 row_newbcast:12 row_mask:0xf bank_mask:0xf bound_ctrl:1
	s_cbranch_vccnz .Lgd2_rare0_7
.Lgd2_back0_7:
	v_cvt_pk_bf16_f32 v54, v48, v49
	v_pk_mul_f32 v[46:47], v[44:45], v[52:53] op_sel_hi:[1,0]
	v_pk_fma_f32 v[6:7], v[80:81], v[46:47], v[6:7] op_sel_hi:[0,1,1]
	v_pk_fma_f32 v[8:9], v[82:83], v[46:47], v[8:9] op_sel_hi:[0,1,1]
	v_pk_fma_f32 v[10:11], v[84:85], v[46:47], v[10:11] op_sel_hi:[0,1,1]
	v_pk_fma_f32 v[12:13], v[86:87], v[46:47], v[12:13] op_sel_hi:[0,1,1]
	v_pk_fma_f32 v[14:15], v[88:89], v[46:47], v[14:15] op_sel_hi:[0,1,1]
	v_pk_fma_f32 v[16:17], v[90:91], v[46:47], v[16:17] op_sel_hi:[0,1,1]
	v_pk_fma_f32 v[18:19], v[92:93], v[46:47], v[18:19] op_sel_hi:[0,1,1]
	v_pk_fma_f32 v[20:21], v[94:95], v[46:47], v[20:21] op_sel_hi:[0,1,1]
	s_mov_b64 exec, s[18:19]
	global_store_dword v154, v54, s[14:15] offset:-4096
	s_mov_b64 exec, -1
	s_waitcnt vmcnt(8)
	v_lshlrev_b32_e32 v116, 16, v108
	v_lshlrev_b32_e32 v117, 16, v109
	v_and_b32_e32 v118, s17, v108
	v_and_b32_e32 v119, s17, v109
	v_lshlrev_b32_e32 v120, 16, v110
	v_and_b32_e32 v121, s17, v110
	v_lshlrev_b32_e32 v122, 16, v111
	v_and_b32_e32 v123, s17, v111
	v_lshlrev_b32_e32 v124, 16, v112
	v_and_b32_e32 v125, s17, v112
	ds_write_b128 v32, v[116:119] offset:33024
	ds_write_b64 v33, v[120:121] offset:33024
	ds_write_b64 v34, v[122:123] offset:33024
	ds_write_b64 v34, v[124:125] offset:33152
	ds_write_b32 v35, v113 offset:33024
	s_add_i32 s16, s16, 8
	s_waitcnt lgkmcnt(0)
	s_barrier
	s_cmpk_lt_u32 s16, 0x800
	s_cbranch_scc0 .Lgd2_done
	global_load_dword v108, v36, s[8:9]
	global_load_dword v109, v36, s[8:9] offset:-2048
	global_load_dword v111, v104, s[8:9] offset:2048
	global_load_dword v110, v37, s[10:11]
	global_load_dword v112, v105, s[10:11]
	global_load_dword v113, v106, s[12:13]
	s_add_u32 s8, s8, 0xc000
	s_addc_u32 s9, s9, 0
	s_add_u32 s10, s10, 0x20000
	s_addc_u32 s11, s11, 0
	s_add_u32 s12, s12, 0x400
	s_addc_u32 s13, s13, 0
	s_waitcnt lgkmcnt(5)
	v_pk_mul_f32 v[38:39], v[6:7], v[56:57] op_sel_hi:[1,0]
	v_pk_mul_f32 v[40:41], v[6:7], v[56:57] op_sel:[0,1] op_sel_hi:[1,1]
	v_pk_fma_f32 v[38:39], v[8:9], v[58:59], v[38:39] op_sel_hi:[1,0,1]
	v_pk_fma_f32 v[40:41], v[8:9], v[58:59], v[40:41] op_sel:[0,1,0] op_sel_hi:[1,1,1]
	s_waitcnt lgkmcnt(4)
	v_pk_fma_f32 v[38:39], v[10:11], v[60:61], v[38:39] op_sel_hi:[1,0,1]
	v_pk_fma_f32 v[40:41], v[10:11], v[60:61], v[40:41] op_sel:[0,1,0] op_sel_hi:[1,1,1]
	v_pk_fma_f32 v[38:39], v[12:13], v[62:63], v[38:39] op_sel_hi:[1,0,1]
	v_pk_fma_f32 v[40:41], v[12:13], v[62:63], v[40:41] op_sel:[0,1,0] op_sel_hi:[1,1,1]
	s_waitcnt lgkmcnt(3)
	v_pk_fma_f32 v[38:39], v[14:15], v[64:65], v[38:39] op_sel_hi:[1,0,1]
	v_pk_fma_f32 v[40:41], v[14:15], v[64:65], v[40:41] op_sel:[0,1,0] op_sel_hi:[1,1,1]
	v_pk_fma_f32 v[38:39], v[16:17], v[66:67], v[38:39] op_sel_hi:[1,0,1]
	v_pk_fma_f32 v[40:41], v[16:17], v[66:67], v[40:41] op_sel:[0,1,0] op_sel_hi:[1,1,1]
	s_waitcnt lgkmcnt(2)
	v_pk_fma_f32 v[38:39], v[18:19], v[68:69], v[38:39] op_sel_hi:[1,0,1]
	v_pk_fma_f32 v[40:41], v[18:19], v[68:69], v[40:41] op_sel:[0,1,0] op_sel_hi:[1,1,1]
	v_pk_fma_f32 v[38:39], v[20:21], v[70:71], v[38:39] op_sel_hi:[1,0,1]
	v_pk_fma_f32 v[40:41], v[20:21], v[70:71], v[40:41] op_sel:[0,1,0] op_sel_hi:[1,1,1]
	s_waitcnt lgkmcnt(0)
	v_mul_f32_e32 v50, v76, v51
	v_add_f32_dpp v38, v38, v38 row_ror:8 row_mask:0xf bank_mask:0x3 bound_ctrl:1
	v_add_f32_dpp v39, v39, v39 row_ror:8 row_mask:0xf bank_mask:0x3 bound_ctrl:1
	v_add_f32_dpp v38, v40, v40 row_ror:8 row_mask:0xf bank_mask:0xc bound_ctrl:1
	v_add_f32_dpp v39, v41, v41 row_ror:8 row_mask:0xf bank_mask:0xc bound_ctrl:1
	ds_read_b128 v[80:83], v2 offset:17664
	v_add_f32_dpp v38, v38, v38 row_half_mirror row_mask:0xf bank_mask:0x5 bound_ctrl:1
	v_add_f32_dpp v38, v39, v39 row_half_mirror row_mask:0xf bank_mask:0xa bound_ctrl:1
	ds_read_b128 v[84:87], v2 offset:17920
	ds_read_b128 v[88:91], v2 offset:18176
	v_add_f32_dpp v38, v38, v38 quad_perm:[1,0,3,2] row_mask:0xf bank_mask:0xf bound_ctrl:1
	ds_read_b128 v[92:95], v2 offset:18432
	ds_read_b64 v[96:97], v3 offset:29184
	v_add_f32_dpp v38, v38, v38 quad_perm:[2,3,0,1] row_mask:0xf bank_mask:0xf bound_ctrl:1
	ds_read_b128 v[100:103], v1 offset:30992
	v_cmp_gt_f32_e32 vcc, 0x2b8cbccc, v50
	v_fmac_f32_dpp v72, -v38, v50 row_newbcast:0 row_mask:0xf bank_mask:0xf bound_ctrl:1
	v_fmac_f32_dpp v73, -v38, v50 row_newbcast:4 row_mask:0xf bank_mask:0xf bound_ctrl:1
	v_pk_mul_f32 v[44:45], v[72:73], v[76:77] op_sel:[0,1] op_sel_hi:[1,1]
	v_pk_mul_f32 v[48:49], v[44:45], v[78:79] op_sel_hi:[1,0]
	v_rcp_f32_e32 v52, v50
	s_add_u32 s14, s14, 0x1000
	s_addc_u32 s15, s15, 0
	v_fmac_f32_dpp v48, v38, v50 row_newbcast:8 row_mask:0xf bank_mask:0xf bound_ctrl:1
	v_fmac_f32_dpp v49, v38, v50 row_newbcast:12 row_mask:0xf bank_mask:0xf bound_ctrl:1
	s_cbranch_vccnz .Lgd2_rare1_0
.Lgd2_back1_0:
	v_cvt_pk_bf16_f32 v54, v48, v49
	v_pk_mul_f32 v[46:47], v[44:45], v[52:53] op_sel_hi:[1,0]
	v_pk_fma_f32 v[6:7], v[56:57], v[46:47], v[6:7] op_sel_hi:[0,1,1]
	v_pk_fma_f32 v[8:9], v[58:59], v[46:47], v[8:9] op_sel_hi:[0,1,1]
	v_pk_fma_f32 v[10:11], v[60:61], v[46:47], v[10:11] op_sel_hi:[0,1,1]
	v_pk_fma_f32 v[12:13], v[62:63], v[46:47], v[12:13] op_sel_hi:[0,1,1]
	v_pk_fma_f32 v[14:15], v[64:65], v[46:47], v[14:15] op_sel_hi:[0,1,1]
	v_pk_fma_f32 v[16:17], v[66:67], v[46:47], v[16:17] op_sel_hi:[0,1,1]
	v_pk_fma_f32 v[18:19], v[68:69], v[46:47], v[18:19] op_sel_hi:[0,1,1]
	v_pk_fma_f32 v[20:21], v[70:71], v[46:47], v[20:21] op_sel_hi:[0,1,1]
	s_mov_b64 exec, s[18:19]
	global_store_dword v154, v54, s[14:15] offset:-4096
	s_mov_b64 exec, -1
	s_waitcnt lgkmcnt(5)
	v_pk_mul_f32 v[38:39], v[6:7], v[80:81] op_sel_hi:[1,0]
	v_pk_mul_f32 v[40:41], v[6:7], v[80:81] op_sel:[0,1] op_sel_hi:[1,1]
	v_pk_fma_f32 v[38:39], v[8:9], v[82:83], v[38:39] op_sel_hi:[1,0,1]
	v_pk_fma_f32 v[40:41], v[8:9], v[82:83], v[40:41] op_sel:[0,1,0] op_sel_hi:[1,1,1]
	s_waitcnt lgkmcnt(4)
	v_pk_fma_f32 v[38:39], v[10:11], v[84:85], v[38:39] op_sel_hi:[1,0,1]
	v_pk_fma_f32 v[40:41], v[10:11], v[84:85], v[40:41] op_sel:[0,1,0] op_sel_hi:[1,1,1]
	v_pk_fma_f32 v[38:39], v[12:13], v[86:87], v[38:39] op_sel_hi:[1,0,1]
	v_pk_fma_f32 v[40:41], v[12:13], v[86:87], v[40:41] op_sel:[0,1,0] op_sel_hi:[1,1,1]
	s_waitcnt lgkmcnt(3)
	v_pk_fma_f32 v[38:39], v[14:15], v[88:89], v[38:39] op_sel_hi:[1,0,1]
	v_pk_fma_f32 v[40:41], v[14:15], v[88:89], v[40:41] op_sel:[0,1,0] op_sel_hi:[1,1,1]
	v_pk_fma_f32 v[38:39], v[16:17], v[90:91], v[38:39] op_sel_hi:[1,0,1]
	v_pk_fma_f32 v[40:41], v[16:17], v[90:91], v[40:41] op_sel:[0,1,0] op_sel_hi:[1,1,1]
	s_waitcnt lgkmcnt(2)
	v_pk_fma_f32 v[38:39], v[18:19], v[92:93], v[38:39] op_sel_hi:[1,0,1]
	v_pk_fma_f32 v[40:41], v[18:19], v[92:93], v[40:41] op_sel:[0,1,0] op_sel_hi:[1,1,1]
	v_pk_fma_f32 v[38:39], v[20:21], v[94:95], v[38:39] op_sel_hi:[1,0,1]
	v_pk_fma_f32 v[40:41], v[20:21], v[94:95], v[40:41] op_sel:[0,1,0] op_sel_hi:[1,1,1]
	s_waitcnt lgkmcnt(0)
	v_mul_f32_e32 v51, v100, v50
	v_add_f32_dpp v38, v38, v38 row_ror:8 row_mask:0xf bank_mask:0x3 bound_ctrl:1
	v_add_f32_dpp v39, v39, v39 row_ror:8 row_mask:0xf bank_mask:0x3 bound_ctrl:1
	v_add_f32_dpp v38, v40, v40 row_ror:8 row_mask:0xf bank_mask:0xc bound_ctrl:1
	v_add_f32_dpp v39, v41, v41 row_ror:8 row_mask:0xf bank_mask:0xc bound_ctrl:1
	ds_read_b128 v[56:59], v2 offset:18688
	v_add_f32_dpp v38, v38, v38 row_half_mirror row_mask:0xf bank_mask:0x5 bound_ctrl:1
	v_add_f32_dpp v38, v39, v39 row_half_mirror row_mask:0xf bank_mask:0xa bound_ctrl:1
	ds_read_b128 v[60:63], v2 offset:18944
	ds_read_b128 v[64:67], v2 offset:19200
	v_add_f32_dpp v38, v38, v38 quad_perm:[1,0,3,2] row_mask:0xf bank_mask:0xf bound_ctrl:1
	ds_read_b128 v[68:71], v2 offset:19456
	ds_read_b64 v[72:73], v3 offset:29440
	v_add_f32_dpp v38, v38, v38 quad_perm:[2,3,0,1] row_mask:0xf bank_mask:0xf bound_ctrl:1
	ds_read_b128 v[76:79], v1 offset:31008
	v_cmp_gt_f32_e32 vcc, 0x2b8cbccc, v51
	v_fmac_f32_dpp v96, -v38, v51 row_newbcast:0 row_mask:0xf bank_mask:0xf bound_ctrl:1
	v_fmac_f32_dpp v97, -v38, v51 row_newbcast:4 row_mask:0xf bank_mask:0xf bound_ctrl:1
	v_pk_mul_f32 v[44:45], v[96:97], v[100:101] op_sel:[0,1] op_sel_hi:[1,1]
	v_pk_mul_f32 v[48:49], v[44:45], v[102:103] op_sel_hi:[1,0]
	v_rcp_f32_e32 v52, v51
	s_add_u32 s14, s14, 0x1000
	s_addc_u32 s15, s15, 0
	v_fmac_f32_dpp v48, v38, v51 row_newbcast:8 row_mask:0xf bank_mask:0xf bound_ctrl:1
	v_fmac_f32_dpp v49, v38, v51 row_newbcast:12 row_mask:0xf bank_mask:0xf bound_ctrl:1
	s_cbranch_vccnz .Lgd2_rare1_1
.Lgd2_back1_1:
	v_cvt_pk_bf16_f32 v54, v48, v49
	v_pk_mul_f32 v[46:47], v[44:45], v[52:53] op_sel_hi:[1,0]
	v_pk_fma_f32 v[6:7], v[80:81], v[46:47], v[6:7] op_sel_hi:[0,1,1]
	v_pk_fma_f32 v[8:9], v[82:83], v[46:47], v[8:9] op_sel_hi:[0,1,1]
	v_pk_fma_f32 v[10:11], v[84:85], v[46:47], v[10:11] op_sel_hi:[0,1,1]
	v_pk_fma_f32 v[12:13], v[86:87], v[46:47], v[12:13] op_sel_hi:[0,1,1]
	v_pk_fma_f32 v[14:15], v[88:89], v[46:47], v[14:15] op_sel_hi:[0,1,1]
	v_pk_fma_f32 v[16:17], v[90:91], v[46:47], v[16:17] op_sel_hi:[0,1,1]
	v_pk_fma_f32 v[18:19], v[92:93], v[46:47], v[18:19] op_sel_hi:[0,1,1]
	v_pk_fma_f32 v[20:21], v[94:95], v[46:47], v[20:21] op_sel_hi:[0,1,1]
	s_mov_b64 exec, s[18:19]
	global_store_dword v154, v54, s[14:15] offset:-4096
	s_mov_b64 exec, -1
	s_waitcnt lgkmcnt(5)
	v_pk_mul_f32 v[38:39], v[6:7], v[56:57] op_sel_hi:[1,0]
	v_pk_mul_f32 v[40:41], v[6:7], v[56:57] op_sel:[0,1] op_sel_hi:[1,1]
	v_pk_fma_f32 v[38:39], v[8:9], v[58:59], v[38:39] op_sel_hi:[1,0,1]
	v_pk_fma_f32 v[40:41], v[8:9], v[58:59], v[40:41] op_sel:[0,1,0] op_sel_hi:[1,1,1]
	s_waitcnt lgkmcnt(4)
	v_pk_fma_f32 v[38:39], v[10:11], v[60:61], v[38:39] op_sel_hi:[1,0,1]
	v_pk_fma_f32 v[40:41], v[10:11], v[60:61], v[40:41] op_sel:[0,1,0] op_sel_hi:[1,1,1]
	v_pk_fma_f32 v[38:39], v[12:13], v[62:63], v[38:39] op_sel_hi:[1,0,1]
	v_pk_fma_f32 v[40:41], v[12:13], v[62:63], v[40:41] op_sel:[0,1,0] op_sel_hi:[1,1,1]
	s_waitcnt lgkmcnt(3)
	v_pk_fma_f32 v[38:39], v[14:15], v[64:65], v[38:39] op_sel_hi:[1,0,1]
	v_pk_fma_f32 v[40:41], v[14:15], v[64:65], v[40:41] op_sel:[0,1,0] op_sel_hi:[1,1,1]
	v_pk_fma_f32 v[38:39], v[16:17], v[66:67], v[38:39] op_sel_hi:[1,0,1]
	v_pk_fma_f32 v[40:41], v[16:17], v[66:67], v[40:41] op_sel:[0,1,0] op_sel_hi:[1,1,1]
	s_waitcnt lgkmcnt(2)
	v_pk_fma_f32 v[38:39], v[18:19], v[68:69], v[38:39] op_sel_hi:[1,0,1]
	v_pk_fma_f32 v[40:41], v[18:19], v[68:69], v[40:41] op_sel:[0,1,0] op_sel_hi:[1,1,1]
	v_pk_fma_f32 v[38:39], v[20:21], v[70:71], v[38:39] op_sel_hi:[1,0,1]
	v_pk_fma_f32 v[40:41], v[20:21], v[70:71], v[40:41] op_sel:[0,1,0] op_sel_hi:[1,1,1]
	s_waitcnt lgkmcnt(0)
	v_mul_f32_e32 v50, v76, v51
	v_add_f32_dpp v38, v38, v38 row_ror:8 row_mask:0xf bank_mask:0x3 bound_ctrl:1
	v_add_f32_dpp v39, v39, v39 row_ror:8 row_mask:0xf bank_mask:0x3 bound_ctrl:1
	v_add_f32_dpp v38, v40, v40 row_ror:8 row_mask:0xf bank_mask:0xc bound_ctrl:1
	v_add_f32_dpp v39, v41, v41 row_ror:8 row_mask:0xf bank_mask:0xc bound_ctrl:1
	ds_read_b128 v[80:83], v2 offset:19712
	v_add_f32_dpp v38, v38, v38 row_half_mirror row_mask:0xf bank_mask:0x5 bound_ctrl:1
	v_add_f32_dpp v38, v39, v39 row_half_mirror row_mask:0xf bank_mask:0xa bound_ctrl:1
	ds_read_b128 v[84:87], v2 offset:19968
	ds_read_b128 v[88:91], v2 offset:20224
	v_add_f32_dpp v38, v38, v38 quad_perm:[1,0,3,2] row_mask:0xf bank_mask:0xf bound_ctrl:1
	ds_read_b128 v[92:95], v2 offset:20480
	ds_read_b64 v[96:97], v3 offset:29696
	v_add_f32_dpp v38, v38, v38 quad_perm:[2,3,0,1] row_mask:0xf bank_mask:0xf bound_ctrl:1
	ds_read_b128 v[100:103], v1 offset:31024
	v_cmp_gt_f32_e32 vcc, 0x2b8cbccc, v50
	v_fmac_f32_dpp v72, -v38, v50 row_newbcast:0 row_mask:0xf bank_mask:0xf bound_ctrl:1
	v_fmac_f32_dpp v73, -v38, v50 row_newbcast:4 row_mask:0xf bank_mask:0xf bound_ctrl:1
	v_pk_mul_f32 v[44:45], v[72:73], v[76:77] op_sel:[0,1] op_sel_hi:[1,1]
	v_pk_mul_f32 v[48:49], v[44:45], v[78:79] op_sel_hi:[1,0]
	v_rcp_f32_e32 v52, v50
	s_add_u32 s14, s14, 0x1000
	s_addc_u32 s15, s15, 0
	v_fmac_f32_dpp v48, v38, v50 row_newbcast:8 row_mask:0xf bank_mask:0xf bound_ctrl:1
	v_fmac_f32_dpp v49, v38, v50 row_newbcast:12 row_mask:0xf bank_mask:0xf bound_ctrl:1
	s_cbranch_vccnz .Lgd2_rare1_2
.Lgd2_back1_2:
	v_cvt_pk_bf16_f32 v54, v48, v49
	v_pk_mul_f32 v[46:47], v[44:45], v[52:53] op_sel_hi:[1,0]
	v_pk_fma_f32 v[6:7], v[56:57], v[46:47], v[6:7] op_sel_hi:[0,1,1]
	v_pk_fma_f32 v[8:9], v[58:59], v[46:47], v[8:9] op_sel_hi:[0,1,1]
	v_pk_fma_f32 v[10:11], v[60:61], v[46:47], v[10:11] op_sel_hi:[0,1,1]
	v_pk_fma_f32 v[12:13], v[62:63], v[46:47], v[12:13] op_sel_hi:[0,1,1]
	v_pk_fma_f32 v[14:15], v[64:65], v[46:47], v[14:15] op_sel_hi:[0,1,1]
	v_pk_fma_f32 v[16:17], v[66:67], v[46:47], v[16:17] op_sel_hi:[0,1,1]
	v_pk_fma_f32 v[18:19], v[68:69], v[46:47], v[18:19] op_sel_hi:[0,1,1]
	v_pk_fma_f32 v[20:21], v[70:71], v[46:47], v[20:21] op_sel_hi:[0,1,1]
	s_mov_b64 exec, s[18:19]
	global_store_dword v154, v54, s[14:15] offset:-4096
	s_mov_b64 exec, -1
	s_waitcnt lgkmcnt(5)
	v_pk_mul_f32 v[38:39], v[6:7], v[80:81] op_sel_hi:[1,0]
	v_pk_mul_f32 v[40:41], v[6:7], v[80:81] op_sel:[0,1] op_sel_hi:[1,1]
	v_pk_fma_f32 v[38:39], v[8:9], v[82:83], v[38:39] op_sel_hi:[1,0,1]
	v_pk_fma_f32 v[40:41], v[8:9], v[82:83], v[40:41] op_sel:[0,1,0] op_sel_hi:[1,1,1]
	s_waitcnt lgkmcnt(4)
	v_pk_fma_f32 v[38:39], v[10:11], v[84:85], v[38:39] op_sel_hi:[1,0,1]
	v_pk_fma_f32 v[40:41], v[10:11], v[84:85], v[40:41] op_sel:[0,1,0] op_sel_hi:[1,1,1]
	v_pk_fma_f32 v[38:39], v[12:13], v[86:87], v[38:39] op_sel_hi:[1,0,1]
	v_pk_fma_f32 v[40:41], v[12:13], v[86:87], v[40:41] op_sel:[0,1,0] op_sel_hi:[1,1,1]
	s_waitcnt lgkmcnt(3)
	v_pk_fma_f32 v[38:39], v[14:15], v[88:89], v[38:39] op_sel_hi:[1,0,1]
	v_pk_fma_f32 v[40:41], v[14:15], v[88:89], v[40:41] op_sel:[0,1,0] op_sel_hi:[1,1,1]
	v_pk_fma_f32 v[38:39], v[16:17], v[90:91], v[38:39] op_sel_hi:[1,0,1]
	v_pk_fma_f32 v[40:41], v[16:17], v[90:91], v[40:41] op_sel:[0,1,0] op_sel_hi:[1,1,1]
	s_waitcnt lgkmcnt(2)
	v_pk_fma_f32 v[38:39], v[18:19], v[92:93], v[38:39] op_sel_hi:[1,0,1]
	v_pk_fma_f32 v[40:41], v[18:19], v[92:93], v[40:41] op_sel:[0,1,0] op_sel_hi:[1,1,1]
	v_pk_fma_f32 v[38:39], v[20:21], v[94:95], v[38:39] op_sel_hi:[1,0,1]
	v_pk_fma_f32 v[40:41], v[20:21], v[94:95], v[40:41] op_sel:[0,1,0] op_sel_hi:[1,1,1]
	s_waitcnt lgkmcnt(0)
	v_mul_f32_e32 v51, v100, v50
	v_add_f32_dpp v38, v38, v38 row_ror:8 row_mask:0xf bank_mask:0x3 bound_ctrl:1
	v_add_f32_dpp v39, v39, v39 row_ror:8 row_mask:0xf bank_mask:0x3 bound_ctrl:1
	v_add_f32_dpp v38, v40, v40 row_ror:8 row_mask:0xf bank_mask:0xc bound_ctrl:1
	v_add_f32_dpp v39, v41, v41 row_ror:8 row_mask:0xf bank_mask:0xc bound_ctrl:1
	ds_read_b128 v[56:59], v2 offset:20736
	v_add_f32_dpp v38, v38, v38 row_half_mirror row_mask:0xf bank_mask:0x5 bound_ctrl:1
	v_add_f32_dpp v38, v39, v39 row_half_mirror row_mask:0xf bank_mask:0xa bound_ctrl:1
	ds_read_b128 v[60:63], v2 offset:20992
	ds_read_b128 v[64:67], v2 offset:21248
	v_add_f32_dpp v38, v38, v38 quad_perm:[1,0,3,2] row_mask:0xf bank_mask:0xf bound_ctrl:1
	ds_read_b128 v[68:71], v2 offset:21504
	ds_read_b64 v[72:73], v3 offset:29952
	v_add_f32_dpp v38, v38, v38 quad_perm:[2,3,0,1] row_mask:0xf bank_mask:0xf bound_ctrl:1
	ds_read_b128 v[76:79], v1 offset:31040
	v_cmp_gt_f32_e32 vcc, 0x2b8cbccc, v51
	v_fmac_f32_dpp v96, -v38, v51 row_newbcast:0 row_mask:0xf bank_mask:0xf bound_ctrl:1
	v_fmac_f32_dpp v97, -v38, v51 row_newbcast:4 row_mask:0xf bank_mask:0xf bound_ctrl:1
	v_pk_mul_f32 v[44:45], v[96:97], v[100:101] op_sel:[0,1] op_sel_hi:[1,1]
	v_pk_mul_f32 v[48:49], v[44:45], v[102:103] op_sel_hi:[1,0]
	v_rcp_f32_e32 v52, v51
	s_add_u32 s14, s14, 0x1000
	s_addc_u32 s15, s15, 0
	v_fmac_f32_dpp v48, v38, v51 row_newbcast:8 row_mask:0xf bank_mask:0xf bound_ctrl:1
	v_fmac_f32_dpp v49, v38, v51 row_newbcast:12 row_mask:0xf bank_mask:0xf bound_ctrl:1
	s_cbranch_vccnz .Lgd2_rare1_3
.Lgd2_back1_3:
	v_cvt_pk_bf16_f32 v54, v48, v49
	v_pk_mul_f32 v[46:47], v[44:45], v[52:53] op_sel_hi:[1,0]
	v_pk_fma_f32 v[6:7], v[80:81], v[46:47], v[6:7] op_sel_hi:[0,1,1]
	v_pk_fma_f32 v[8:9], v[82:83], v[46:47], v[8:9] op_sel_hi:[0,1,1]
	v_pk_fma_f32 v[10:11], v[84:85], v[46:47], v[10:11] op_sel_hi:[0,1,1]
	v_pk_fma_f32 v[12:13], v[86:87], v[46:47], v[12:13] op_sel_hi:[0,1,1]
	v_pk_fma_f32 v[14:15], v[88:89], v[46:47], v[14:15] op_sel_hi:[0,1,1]
	v_pk_fma_f32 v[16:17], v[90:91], v[46:47], v[16:17] op_sel_hi:[0,1,1]
	v_pk_fma_f32 v[18:19], v[92:93], v[46:47], v[18:19] op_sel_hi:[0,1,1]
	v_pk_fma_f32 v[20:21], v[94:95], v[46:47], v[20:21] op_sel_hi:[0,1,1]
	s_mov_b64 exec, s[18:19]
	global_store_dword v154, v54, s[14:15] offset:-4096
	s_mov_b64 exec, -1
	s_waitcnt lgkmcnt(5)
	v_pk_mul_f32 v[38:39], v[6:7], v[56:57] op_sel_hi:[1,0]
	v_pk_mul_f32 v[40:41], v[6:7], v[56:57] op_sel:[0,1] op_sel_hi:[1,1]
	v_pk_fma_f32 v[38:39], v[8:9], v[58:59], v[38:39] op_sel_hi:[1,0,1]
	v_pk_fma_f32 v[40:41], v[8:9], v[58:59], v[40:41] op_sel:[0,1,0] op_sel_hi:[1,1,1]
	s_waitcnt lgkmcnt(4)
	v_pk_fma_f32 v[38:39], v[10:11], v[60:61], v[38:39] op_sel_hi:[1,0,1]
	v_pk_fma_f32 v[40:41], v[10:11], v[60:61], v[40:41] op_sel:[0,1,0] op_sel_hi:[1,1,1]
	v_pk_fma_f32 v[38:39], v[12:13], v[62:63], v[38:39] op_sel_hi:[1,0,1]
	v_pk_fma_f32 v[40:41], v[12:13], v[62:63], v[40:41] op_sel:[0,1,0] op_sel_hi:[1,1,1]
	s_waitcnt lgkmcnt(3)
	v_pk_fma_f32 v[38:39], v[14:15], v[64:65], v[38:39] op_sel_hi:[1,0,1]
	v_pk_fma_f32 v[40:41], v[14:15], v[64:65], v[40:41] op_sel:[0,1,0] op_sel_hi:[1,1,1]
	v_pk_fma_f32 v[38:39], v[16:17], v[66:67], v[38:39] op_sel_hi:[1,0,1]
	v_pk_fma_f32 v[40:41], v[16:17], v[66:67], v[40:41] op_sel:[0,1,0] op_sel_hi:[1,1,1]
	s_waitcnt lgkmcnt(2)
	v_pk_fma_f32 v[38:39], v[18:19], v[68:69], v[38:39] op_sel_hi:[1,0,1]
	v_pk_fma_f32 v[40:41], v[18:19], v[68:69], v[40:41] op_sel:[0,1,0] op_sel_hi:[1,1,1]
	v_pk_fma_f32 v[38:39], v[20:21], v[70:71], v[38:39] op_sel_hi:[1,0,1]
	v_pk_fma_f32 v[40:41], v[20:21], v[70:71], v[40:41] op_sel:[0,1,0] op_sel_hi:[1,1,1]
	s_waitcnt lgkmcnt(0)
	v_mul_f32_e32 v50, v76, v51
	v_add_f32_dpp v38, v38, v38 row_ror:8 row_mask:0xf bank_mask:0x3 bound_ctrl:1
	v_add_f32_dpp v39, v39, v39 row_ror:8 row_mask:0xf bank_mask:0x3 bound_ctrl:1
	v_add_f32_dpp v38, v40, v40 row_ror:8 row_mask:0xf bank_mask:0xc bound_ctrl:1
	v_add_f32_dpp v39, v41, v41 row_ror:8 row_mask:0xf bank_mask:0xc bound_ctrl:1
	ds_read_b128 v[80:83], v2 offset:21760
	v_add_f32_dpp v38, v38, v38 row_half_mirror row_mask:0xf bank_mask:0x5 bound_ctrl:1
	v_add_f32_dpp v38, v39, v39 row_half_mirror row_mask:0xf bank_mask:0xa bound_ctrl:1
	ds_read_b128 v[84:87], v2 offset:22016
	ds_read_b128 v[88:91], v2 offset:22272
	v_add_f32_dpp v38, v38, v38 quad_perm:[1,0,3,2] row_mask:0xf bank_mask:0xf bound_ctrl:1
	ds_read_b128 v[92:95], v2 offset:22528
	ds_read_b64 v[96:97], v3 offset:30208
	v_add_f32_dpp v38, v38, v38 quad_perm:[2,3,0,1] row_mask:0xf bank_mask:0xf bound_ctrl:1
	ds_read_b128 v[100:103], v1 offset:31056
	v_cmp_gt_f32_e32 vcc, 0x2b8cbccc, v50
	v_fmac_f32_dpp v72, -v38, v50 row_newbcast:0 row_mask:0xf bank_mask:0xf bound_ctrl:1
	v_fmac_f32_dpp v73, -v38, v50 row_newbcast:4 row_mask:0xf bank_mask:0xf bound_ctrl:1
	v_pk_mul_f32 v[44:45], v[72:73], v[76:77] op_sel:[0,1] op_sel_hi:[1,1]
	v_pk_mul_f32 v[48:49], v[44:45], v[78:79] op_sel_hi:[1,0]
	v_rcp_f32_e32 v52, v50
	s_add_u32 s14, s14, 0x1000
	s_addc_u32 s15, s15, 0
	v_fmac_f32_dpp v48, v38, v50 row_newbcast:8 row_mask:0xf bank_mask:0xf bound_ctrl:1
	v_fmac_f32_dpp v49, v38, v50 row_newbcast:12 row_mask:0xf bank_mask:0xf bound_ctrl:1
	s_cbranch_vccnz .Lgd2_rare1_4
.Lgd2_back1_4:
	v_cvt_pk_bf16_f32 v54, v48, v49
	v_pk_mul_f32 v[46:47], v[44:45], v[52:53] op_sel_hi:[1,0]
	v_pk_fma_f32 v[6:7], v[56:57], v[46:47], v[6:7] op_sel_hi:[0,1,1]
	v_pk_fma_f32 v[8:9], v[58:59], v[46:47], v[8:9] op_sel_hi:[0,1,1]
	v_pk_fma_f32 v[10:11], v[60:61], v[46:47], v[10:11] op_sel_hi:[0,1,1]
	v_pk_fma_f32 v[12:13], v[62:63], v[46:47], v[12:13] op_sel_hi:[0,1,1]
	v_pk_fma_f32 v[14:15], v[64:65], v[46:47], v[14:15] op_sel_hi:[0,1,1]
	v_pk_fma_f32 v[16:17], v[66:67], v[46:47], v[16:17] op_sel_hi:[0,1,1]
	v_pk_fma_f32 v[18:19], v[68:69], v[46:47], v[18:19] op_sel_hi:[0,1,1]
	v_pk_fma_f32 v[20:21], v[70:71], v[46:47], v[20:21] op_sel_hi:[0,1,1]
	s_mov_b64 exec, s[18:19]
	global_store_dword v154, v54, s[14:15] offset:-4096
	s_mov_b64 exec, -1
	s_waitcnt lgkmcnt(5)
	v_pk_mul_f32 v[38:39], v[6:7], v[80:81] op_sel_hi:[1,0]
	v_pk_mul_f32 v[40:41], v[6:7], v[80:81] op_sel:[0,1] op_sel_hi:[1,1]
	v_pk_fma_f32 v[38:39], v[8:9], v[82:83], v[38:39] op_sel_hi:[1,0,1]
	v_pk_fma_f32 v[40:41], v[8:9], v[82:83], v[40:41] op_sel:[0,1,0] op_sel_hi:[1,1,1]
	s_waitcnt lgkmcnt(4)
	v_pk_fma_f32 v[38:39], v[10:11], v[84:85], v[38:39] op_sel_hi:[1,0,1]
	v_pk_fma_f32 v[40:41], v[10:11], v[84:85], v[40:41] op_sel:[0,1,0] op_sel_hi:[1,1,1]
	v_pk_fma_f32 v[38:39], v[12:13], v[86:87], v[38:39] op_sel_hi:[1,0,1]
	v_pk_fma_f32 v[40:41], v[12:13], v[86:87], v[40:41] op_sel:[0,1,0] op_sel_hi:[1,1,1]
	s_waitcnt lgkmcnt(3)
	v_pk_fma_f32 v[38:39], v[14:15], v[88:89], v[38:39] op_sel_hi:[1,0,1]
	v_pk_fma_f32 v[40:41], v[14:15], v[88:89], v[40:41] op_sel:[0,1,0] op_sel_hi:[1,1,1]
	v_pk_fma_f32 v[38:39], v[16:17], v[90:91], v[38:39] op_sel_hi:[1,0,1]
	v_pk_fma_f32 v[40:41], v[16:17], v[90:91], v[40:41] op_sel:[0,1,0] op_sel_hi:[1,1,1]
	s_waitcnt lgkmcnt(2)
	v_pk_fma_f32 v[38:39], v[18:19], v[92:93], v[38:39] op_sel_hi:[1,0,1]
	v_pk_fma_f32 v[40:41], v[18:19], v[92:93], v[40:41] op_sel:[0,1,0] op_sel_hi:[1,1,1]
	v_pk_fma_f32 v[38:39], v[20:21], v[94:95], v[38:39] op_sel_hi:[1,0,1]
	v_pk_fma_f32 v[40:41], v[20:21], v[94:95], v[40:41] op_sel:[0,1,0] op_sel_hi:[1,1,1]
	s_waitcnt lgkmcnt(0)
	v_mul_f32_e32 v51, v100, v50
	v_add_f32_dpp v38, v38, v38 row_ror:8 row_mask:0xf bank_mask:0x3 bound_ctrl:1
	v_add_f32_dpp v39, v39, v39 row_ror:8 row_mask:0xf bank_mask:0x3 bound_ctrl:1
	v_add_f32_dpp v38, v40, v40 row_ror:8 row_mask:0xf bank_mask:0xc bound_ctrl:1
	v_add_f32_dpp v39, v41, v41 row_ror:8 row_mask:0xf bank_mask:0xc bound_ctrl:1
	ds_read_b128 v[56:59], v2 offset:22784
	v_add_f32_dpp v38, v38, v38 row_half_mirror row_mask:0xf bank_mask:0x5 bound_ctrl:1
	v_add_f32_dpp v38, v39, v39 row_half_mirror row_mask:0xf bank_mask:0xa bound_ctrl:1
	ds_read_b128 v[60:63], v2 offset:23040
	ds_read_b128 v[64:67], v2 offset:23296
	v_add_f32_dpp v38, v38, v38 quad_perm:[1,0,3,2] row_mask:0xf bank_mask:0xf bound_ctrl:1
	ds_read_b128 v[68:71], v2 offset:23552
	ds_read_b64 v[72:73], v3 offset:30464
	v_add_f32_dpp v38, v38, v38 quad_perm:[2,3,0,1] row_mask:0xf bank_mask:0xf bound_ctrl:1
	ds_read_b128 v[76:79], v1 offset:31072
	v_cmp_gt_f32_e32 vcc, 0x2b8cbccc, v51
	v_fmac_f32_dpp v96, -v38, v51 row_newbcast:0 row_mask:0xf bank_mask:0xf bound_ctrl:1
	v_fmac_f32_dpp v97, -v38, v51 row_newbcast:4 row_mask:0xf bank_mask:0xf bound_ctrl:1
	v_pk_mul_f32 v[44:45], v[96:97], v[100:101] op_sel:[0,1] op_sel_hi:[1,1]
	v_pk_mul_f32 v[48:49], v[44:45], v[102:103] op_sel_hi:[1,0]
	v_rcp_f32_e32 v52, v51
	s_add_u32 s14, s14, 0x1000
	s_addc_u32 s15, s15, 0
	v_fmac_f32_dpp v48, v38, v51 row_newbcast:8 row_mask:0xf bank_mask:0xf bound_ctrl:1
	v_fmac_f32_dpp v49, v38, v51 row_newbcast:12 row_mask:0xf bank_mask:0xf bound_ctrl:1
	s_cbranch_vccnz .Lgd2_rare1_5
.Lgd2_back1_5:
	v_cvt_pk_bf16_f32 v54, v48, v49
	v_pk_mul_f32 v[46:47], v[44:45], v[52:53] op_sel_hi:[1,0]
	v_pk_fma_f32 v[6:7], v[80:81], v[46:47], v[6:7] op_sel_hi:[0,1,1]
	v_pk_fma_f32 v[8:9], v[82:83], v[46:47], v[8:9] op_sel_hi:[0,1,1]
	v_pk_fma_f32 v[10:11], v[84:85], v[46:47], v[10:11] op_sel_hi:[0,1,1]
	v_pk_fma_f32 v[12:13], v[86:87], v[46:47], v[12:13] op_sel_hi:[0,1,1]
	v_pk_fma_f32 v[14:15], v[88:89], v[46:47], v[14:15] op_sel_hi:[0,1,1]
	v_pk_fma_f32 v[16:17], v[90:91], v[46:47], v[16:17] op_sel_hi:[0,1,1]
	v_pk_fma_f32 v[18:19], v[92:93], v[46:47], v[18:19] op_sel_hi:[0,1,1]
	v_pk_fma_f32 v[20:21], v[94:95], v[46:47], v[20:21] op_sel_hi:[0,1,1]
	s_mov_b64 exec, s[18:19]
	global_store_dword v154, v54, s[14:15] offset:-4096
	s_mov_b64 exec, -1
	s_waitcnt lgkmcnt(5)
	v_pk_mul_f32 v[38:39], v[6:7], v[56:57] op_sel_hi:[1,0]
	v_pk_mul_f32 v[40:41], v[6:7], v[56:57] op_sel:[0,1] op_sel_hi:[1,1]
	v_pk_fma_f32 v[38:39], v[8:9], v[58:59], v[38:39] op_sel_hi:[1,0,1]
	v_pk_fma_f32 v[40:41], v[8:9], v[58:59], v[40:41] op_sel:[0,1,0] op_sel_hi:[1,1,1]
	s_waitcnt lgkmcnt(4)
	v_pk_fma_f32 v[38:39], v[10:11], v[60:61], v[38:39] op_sel_hi:[1,0,1]
	v_pk_fma_f32 v[40:41], v[10:11], v[60:61], v[40:41] op_sel:[0,1,0] op_sel_hi:[1,1,1]
	v_pk_fma_f32 v[38:39], v[12:13], v[62:63], v[38:39] op_sel_hi:[1,0,1]
	v_pk_fma_f32 v[40:41], v[12:13], v[62:63], v[40:41] op_sel:[0,1,0] op_sel_hi:[1,1,1]
	s_waitcnt lgkmcnt(3)
	v_pk_fma_f32 v[38:39], v[14:15], v[64:65], v[38:39] op_sel_hi:[1,0,1]
	v_pk_fma_f32 v[40:41], v[14:15], v[64:65], v[40:41] op_sel:[0,1,0] op_sel_hi:[1,1,1]
	v_pk_fma_f32 v[38:39], v[16:17], v[66:67], v[38:39] op_sel_hi:[1,0,1]
	v_pk_fma_f32 v[40:41], v[16:17], v[66:67], v[40:41] op_sel:[0,1,0] op_sel_hi:[1,1,1]
	s_waitcnt lgkmcnt(2)
	v_pk_fma_f32 v[38:39], v[18:19], v[68:69], v[38:39] op_sel_hi:[1,0,1]
	v_pk_fma_f32 v[40:41], v[18:19], v[68:69], v[40:41] op_sel:[0,1,0] op_sel_hi:[1,1,1]
	v_pk_fma_f32 v[38:39], v[20:21], v[70:71], v[38:39] op_sel_hi:[1,0,1]
	v_pk_fma_f32 v[40:41], v[20:21], v[70:71], v[40:41] op_sel:[0,1,0] op_sel_hi:[1,1,1]
	s_waitcnt lgkmcnt(0)
	v_mul_f32_e32 v50, v76, v51
	v_add_f32_dpp v38, v38, v38 row_ror:8 row_mask:0xf bank_mask:0x3 bound_ctrl:1
	v_add_f32_dpp v39, v39, v39 row_ror:8 row_mask:0xf bank_mask:0x3 bound_ctrl:1
	v_add_f32_dpp v38, v40, v40 row_ror:8 row_mask:0xf bank_mask:0xc bound_ctrl:1
	v_add_f32_dpp v39, v41, v41 row_ror:8 row_mask:0xf bank_mask:0xc bound_ctrl:1
	ds_read_b128 v[80:83], v2 offset:23808
	v_add_f32_dpp v38, v38, v38 row_half_mirror row_mask:0xf bank_mask:0x5 bound_ctrl:1
	v_add_f32_dpp v38, v39, v39 row_half_mirror row_mask:0xf bank_mask:0xa bound_ctrl:1
	ds_read_b128 v[84:87], v2 offset:24064
	ds_read_b128 v[88:91], v2 offset:24320
	v_add_f32_dpp v38, v38, v38 quad_perm:[1,0,3,2] row_mask:0xf bank_mask:0xf bound_ctrl:1
	ds_read_b128 v[92:95], v2 offset:24576
	ds_read_b64 v[96:97], v3 offset:30720
	v_add_f32_dpp v38, v38, v38 quad_perm:[2,3,0,1] row_mask:0xf bank_mask:0xf bound_ctrl:1
	ds_read_b128 v[100:103], v1 offset:31088
	v_cmp_gt_f32_e32 vcc, 0x2b8cbccc, v50
	v_fmac_f32_dpp v72, -v38, v50 row_newbcast:0 row_mask:0xf bank_mask:0xf bound_ctrl:1
	v_fmac_f32_dpp v73, -v38, v50 row_newbcast:4 row_mask:0xf bank_mask:0xf bound_ctrl:1
	v_pk_mul_f32 v[44:45], v[72:73], v[76:77] op_sel:[0,1] op_sel_hi:[1,1]
	v_pk_mul_f32 v[48:49], v[44:45], v[78:79] op_sel_hi:[1,0]
	v_rcp_f32_e32 v52, v50
	s_add_u32 s14, s14, 0x1000
	s_addc_u32 s15, s15, 0
	v_fmac_f32_dpp v48, v38, v50 row_newbcast:8 row_mask:0xf bank_mask:0xf bound_ctrl:1
	v_fmac_f32_dpp v49, v38, v50 row_newbcast:12 row_mask:0xf bank_mask:0xf bound_ctrl:1
	s_cbranch_vccnz .Lgd2_rare1_6
.Lgd2_back1_6:
	v_cvt_pk_bf16_f32 v54, v48, v49
	v_pk_mul_f32 v[46:47], v[44:45], v[52:53] op_sel_hi:[1,0]
	v_pk_fma_f32 v[6:7], v[56:57], v[46:47], v[6:7] op_sel_hi:[0,1,1]
	v_pk_fma_f32 v[8:9], v[58:59], v[46:47], v[8:9] op_sel_hi:[0,1,1]
	v_pk_fma_f32 v[10:11], v[60:61], v[46:47], v[10:11] op_sel_hi:[0,1,1]
	v_pk_fma_f32 v[12:13], v[62:63], v[46:47], v[12:13] op_sel_hi:[0,1,1]
	v_pk_fma_f32 v[14:15], v[64:65], v[46:47], v[14:15] op_sel_hi:[0,1,1]
	v_pk_fma_f32 v[16:17], v[66:67], v[46:47], v[16:17] op_sel_hi:[0,1,1]
	v_pk_fma_f32 v[18:19], v[68:69], v[46:47], v[18:19] op_sel_hi:[0,1,1]
	v_pk_fma_f32 v[20:21], v[70:71], v[46:47], v[20:21] op_sel_hi:[0,1,1]
	s_mov_b64 exec, s[18:19]
	global_store_dword v154, v54, s[14:15] offset:-4096
	s_mov_b64 exec, -1
	s_waitcnt lgkmcnt(5)
	v_pk_mul_f32 v[38:39], v[6:7], v[80:81] op_sel_hi:[1,0]
	v_pk_mul_f32 v[40:41], v[6:7], v[80:81] op_sel:[0,1] op_sel_hi:[1,1]
	v_pk_fma_f32 v[38:39], v[8:9], v[82:83], v[38:39] op_sel_hi:[1,0,1]
	v_pk_fma_f32 v[40:41], v[8:9], v[82:83], v[40:41] op_sel:[0,1,0] op_sel_hi:[1,1,1]
	s_waitcnt lgkmcnt(4)
	v_pk_fma_f32 v[38:39], v[10:11], v[84:85], v[38:39] op_sel_hi:[1,0,1]
	v_pk_fma_f32 v[40:41], v[10:11], v[84:85], v[40:41] op_sel:[0,1,0] op_sel_hi:[1,1,1]
	v_pk_fma_f32 v[38:39], v[12:13], v[86:87], v[38:39] op_sel_hi:[1,0,1]
	v_pk_fma_f32 v[40:41], v[12:13], v[86:87], v[40:41] op_sel:[0,1,0] op_sel_hi:[1,1,1]
	s_waitcnt lgkmcnt(3)
	v_pk_fma_f32 v[38:39], v[14:15], v[88:89], v[38:39] op_sel_hi:[1,0,1]
	v_pk_fma_f32 v[40:41], v[14:15], v[88:89], v[40:41] op_sel:[0,1,0] op_sel_hi:[1,1,1]
	v_pk_fma_f32 v[38:39], v[16:17], v[90:91], v[38:39] op_sel_hi:[1,0,1]
	v_pk_fma_f32 v[40:41], v[16:17], v[90:91], v[40:41] op_sel:[0,1,0] op_sel_hi:[1,1,1]
	s_waitcnt lgkmcnt(2)
	v_pk_fma_f32 v[38:39], v[18:19], v[92:93], v[38:39] op_sel_hi:[1,0,1]
	v_pk_fma_f32 v[40:41], v[18:19], v[92:93], v[40:41] op_sel:[0,1,0] op_sel_hi:[1,1,1]
	v_pk_fma_f32 v[38:39], v[20:21], v[94:95], v[38:39] op_sel_hi:[1,0,1]
	v_pk_fma_f32 v[40:41], v[20:21], v[94:95], v[40:41] op_sel:[0,1,0] op_sel_hi:[1,1,1]
	s_waitcnt lgkmcnt(0)
	v_mul_f32_e32 v51, v100, v50
	v_add_f32_dpp v38, v38, v38 row_ror:8 row_mask:0xf bank_mask:0x3 bound_ctrl:1
	v_add_f32_dpp v39, v39, v39 row_ror:8 row_mask:0xf bank_mask:0x3 bound_ctrl:1
	v_add_f32_dpp v38, v40, v40 row_ror:8 row_mask:0xf bank_mask:0xc bound_ctrl:1
	v_add_f32_dpp v39, v41, v41 row_ror:8 row_mask:0xf bank_mask:0xc bound_ctrl:1
	ds_read_b128 v[56:59], v2 offset:33024
	v_add_f32_dpp v38, v38, v38 row_half_mirror row_mask:0xf bank_mask:0x5 bound_ctrl:1
	v_add_f32_dpp v38, v39, v39 row_half_mirror row_mask:0xf bank_mask:0xa bound_ctrl:1
	ds_read_b128 v[60:63], v2 offset:33280
	ds_read_b128 v[64:67], v2 offset:33536
	v_add_f32_dpp v38, v38, v38 quad_perm:[1,0,3,2] row_mask:0xf bank_mask:0xf bound_ctrl:1
	ds_read_b128 v[68:71], v2 offset:33792
	ds_read_b64 v[72:73], v3 offset:45312
	v_add_f32_dpp v38, v38, v38 quad_perm:[2,3,0,1] row_mask:0xf bank_mask:0xf bound_ctrl:1
	ds_read_b128 v[76:79], v1 offset:47360
	v_cmp_gt_f32_e32 vcc, 0x2b8cbccc, v51
	v_fmac_f32_dpp v96, -v38, v51 row_newbcast:0 row_mask:0xf bank_mask:0xf bound_ctrl:1
	v_fmac_f32_dpp v97, -v38, v51 row_newbcast:4 row_mask:0xf bank_mask:0xf bound_ctrl:1
	v_pk_mul_f32 v[44:45], v[96:97], v[100:101] op_sel:[0,1] op_sel_hi:[1,1]
	v_pk_mul_f32 v[48:49], v[44:45], v[102:103] op_sel_hi:[1,0]
	v_rcp_f32_e32 v52, v51
	s_add_u32 s14, s14, 0x1000
	s_addc_u32 s15, s15, 0
	v_fmac_f32_dpp v48, v38, v51 row_newbcast:8 row_mask:0xf bank_mask:0xf bound_ctrl:1
	v_fmac_f32_dpp v49, v38, v51 row_newbcast:12 row_mask:0xf bank_mask:0xf bound_ctrl:1
	s_cbranch_vccnz .Lgd2_rare1_7
.Lgd2_back1_7:
	v_cvt_pk_bf16_f32 v54, v48, v49
	v_pk_mul_f32 v[46:47], v[44:45], v[52:53] op_sel_hi:[1,0]
	v_pk_fma_f32 v[6:7], v[80:81], v[46:47], v[6:7] op_sel_hi:[0,1,1]
	v_pk_fma_f32 v[8:9], v[82:83], v[46:47], v[8:9] op_sel_hi:[0,1,1]
	v_pk_fma_f32 v[10:11], v[84:85], v[46:47], v[10:11] op_sel_hi:[0,1,1]
	v_pk_fma_f32 v[12:13], v[86:87], v[46:47], v[12:13] op_sel_hi:[0,1,1]
	v_pk_fma_f32 v[14:15], v[88:89], v[46:47], v[14:15] op_sel_hi:[0,1,1]
	v_pk_fma_f32 v[16:17], v[90:91], v[46:47], v[16:17] op_sel_hi:[0,1,1]
	v_pk_fma_f32 v[18:19], v[92:93], v[46:47], v[18:19] op_sel_hi:[0,1,1]
	v_pk_fma_f32 v[20:21], v[94:95], v[46:47], v[20:21] op_sel_hi:[0,1,1]
	s_mov_b64 exec, s[18:19]
	global_store_dword v154, v54, s[14:15] offset:-4096
	s_mov_b64 exec, -1
	s_waitcnt vmcnt(8)
	v_lshlrev_b32_e32 v116, 16, v108
	v_lshlrev_b32_e32 v117, 16, v109
	v_and_b32_e32 v118, s17, v108
	v_and_b32_e32 v119, s17, v109
	v_lshlrev_b32_e32 v120, 16, v110
	v_and_b32_e32 v121, s17, v110
	v_lshlrev_b32_e32 v122, 16, v111
	v_and_b32_e32 v123, s17, v111
	v_lshlrev_b32_e32 v124, 16, v112
	v_and_b32_e32 v125, s17, v112
	ds_write_b128 v32, v[116:119] offset:256
	ds_write_b64 v33, v[120:121] offset:256
	ds_write_b64 v34, v[122:123] offset:256
	ds_write_b64 v34, v[124:125] offset:384
	ds_write_b32 v35, v113 offset:256
	s_add_i32 s16, s16, 8
	s_waitcnt lgkmcnt(0)
	s_barrier
	s_cmpk_lt_u32 s16, 0x800
	s_cbranch_scc0 .Lgd2_done
	global_load_dword v108, v36, s[8:9]
	global_load_dword v109, v36, s[8:9] offset:-2048
	global_load_dword v111, v104, s[8:9] offset:2048
	global_load_dword v110, v37, s[10:11]
	global_load_dword v112, v105, s[10:11]
	global_load_dword v113, v106, s[12:13]
	s_add_u32 s8, s8, 0xc000
	s_addc_u32 s9, s9, 0
	s_add_u32 s10, s10, 0x20000
	s_addc_u32 s11, s11, 0
	s_add_u32 s12, s12, 0x400
	s_addc_u32 s13, s13, 0
	s_waitcnt lgkmcnt(5)
	v_pk_mul_f32 v[38:39], v[6:7], v[56:57] op_sel_hi:[1,0]
	v_pk_mul_f32 v[40:41], v[6:7], v[56:57] op_sel:[0,1] op_sel_hi:[1,1]
	v_pk_fma_f32 v[38:39], v[8:9], v[58:59], v[38:39] op_sel_hi:[1,0,1]
	v_pk_fma_f32 v[40:41], v[8:9], v[58:59], v[40:41] op_sel:[0,1,0] op_sel_hi:[1,1,1]
	s_waitcnt lgkmcnt(4)
	v_pk_fma_f32 v[38:39], v[10:11], v[60:61], v[38:39] op_sel_hi:[1,0,1]
	v_pk_fma_f32 v[40:41], v[10:11], v[60:61], v[40:41] op_sel:[0,1,0] op_sel_hi:[1,1,1]
	v_pk_fma_f32 v[38:39], v[12:13], v[62:63], v[38:39] op_sel_hi:[1,0,1]
	v_pk_fma_f32 v[40:41], v[12:13], v[62:63], v[40:41] op_sel:[0,1,0] op_sel_hi:[1,1,1]
	s_waitcnt lgkmcnt(3)
	v_pk_fma_f32 v[38:39], v[14:15], v[64:65], v[38:39] op_sel_hi:[1,0,1]
	v_pk_fma_f32 v[40:41], v[14:15], v[64:65], v[40:41] op_sel:[0,1,0] op_sel_hi:[1,1,1]
	v_pk_fma_f32 v[38:39], v[16:17], v[66:67], v[38:39] op_sel_hi:[1,0,1]
	v_pk_fma_f32 v[40:41], v[16:17], v[66:67], v[40:41] op_sel:[0,1,0] op_sel_hi:[1,1,1]
	s_waitcnt lgkmcnt(2)
	v_pk_fma_f32 v[38:39], v[18:19], v[68:69], v[38:39] op_sel_hi:[1,0,1]
	v_pk_fma_f32 v[40:41], v[18:19], v[68:69], v[40:41] op_sel:[0,1,0] op_sel_hi:[1,1,1]
	v_pk_fma_f32 v[38:39], v[20:21], v[70:71], v[38:39] op_sel_hi:[1,0,1]
	v_pk_fma_f32 v[40:41], v[20:21], v[70:71], v[40:41] op_sel:[0,1,0] op_sel_hi:[1,1,1]
	s_waitcnt lgkmcnt(0)
	v_mul_f32_e32 v50, v76, v51
	v_add_f32_dpp v38, v38, v38 row_ror:8 row_mask:0xf bank_mask:0x3 bound_ctrl:1
	v_add_f32_dpp v39, v39, v39 row_ror:8 row_mask:0xf bank_mask:0x3 bound_ctrl:1
	v_add_f32_dpp v38, v40, v40 row_ror:8 row_mask:0xf bank_mask:0xc bound_ctrl:1
	v_add_f32_dpp v39, v41, v41 row_ror:8 row_mask:0xf bank_mask:0xc bound_ctrl:1
	ds_read_b128 v[80:83], v2 offset:34048
	v_add_f32_dpp v38, v38, v38 row_half_mirror row_mask:0xf bank_mask:0x5 bound_ctrl:1
	v_add_f32_dpp v38, v39, v39 row_half_mirror row_mask:0xf bank_mask:0xa bound_ctrl:1
	ds_read_b128 v[84:87], v2 offset:34304
	ds_read_b128 v[88:91], v2 offset:34560
	v_add_f32_dpp v38, v38, v38 quad_perm:[1,0,3,2] row_mask:0xf bank_mask:0xf bound_ctrl:1
	ds_read_b128 v[92:95], v2 offset:34816
	ds_read_b64 v[96:97], v3 offset:45568
	v_add_f32_dpp v38, v38, v38 quad_perm:[2,3,0,1] row_mask:0xf bank_mask:0xf bound_ctrl:1
	ds_read_b128 v[100:103], v1 offset:47376
	v_cmp_gt_f32_e32 vcc, 0x2b8cbccc, v50
	v_fmac_f32_dpp v72, -v38, v50 row_newbcast:0 row_mask:0xf bank_mask:0xf bound_ctrl:1
	v_fmac_f32_dpp v73, -v38, v50 row_newbcast:4 row_mask:0xf bank_mask:0xf bound_ctrl:1
	v_pk_mul_f32 v[44:45], v[72:73], v[76:77] op_sel:[0,1] op_sel_hi:[1,1]
	v_pk_mul_f32 v[48:49], v[44:45], v[78:79] op_sel_hi:[1,0]
	v_rcp_f32_e32 v52, v50
	s_add_u32 s14, s14, 0x1000
	s_addc_u32 s15, s15, 0
	v_fmac_f32_dpp v48, v38, v50 row_newbcast:8 row_mask:0xf bank_mask:0xf bound_ctrl:1
	v_fmac_f32_dpp v49, v38, v50 row_newbcast:12 row_mask:0xf bank_mask:0xf bound_ctrl:1
	s_cbranch_vccnz .Lgd2_rare2_0
.Lgd2_back2_0:
	v_cvt_pk_bf16_f32 v54, v48, v49
	v_pk_mul_f32 v[46:47], v[44:45], v[52:53] op_sel_hi:[1,0]
	v_pk_fma_f32 v[6:7], v[56:57], v[46:47], v[6:7] op_sel_hi:[0,1,1]
	v_pk_fma_f32 v[8:9], v[58:59], v[46:47], v[8:9] op_sel_hi:[0,1,1]
	v_pk_fma_f32 v[10:11], v[60:61], v[46:47], v[10:11] op_sel_hi:[0,1,1]
	v_pk_fma_f32 v[12:13], v[62:63], v[46:47], v[12:13] op_sel_hi:[0,1,1]
	v_pk_fma_f32 v[14:15], v[64:65], v[46:47], v[14:15] op_sel_hi:[0,1,1]
	v_pk_fma_f32 v[16:17], v[66:67], v[46:47], v[16:17] op_sel_hi:[0,1,1]
	v_pk_fma_f32 v[18:19], v[68:69], v[46:47], v[18:19] op_sel_hi:[0,1,1]
	v_pk_fma_f32 v[20:21], v[70:71], v[46:47], v[20:21] op_sel_hi:[0,1,1]
	s_mov_b64 exec, s[18:19]
	global_store_dword v154, v54, s[14:15] offset:-4096
	s_mov_b64 exec, -1
	s_waitcnt lgkmcnt(5)
	v_pk_mul_f32 v[38:39], v[6:7], v[80:81] op_sel_hi:[1,0]
	v_pk_mul_f32 v[40:41], v[6:7], v[80:81] op_sel:[0,1] op_sel_hi:[1,1]
	v_pk_fma_f32 v[38:39], v[8:9], v[82:83], v[38:39] op_sel_hi:[1,0,1]
	v_pk_fma_f32 v[40:41], v[8:9], v[82:83], v[40:41] op_sel:[0,1,0] op_sel_hi:[1,1,1]
	s_waitcnt lgkmcnt(4)
	v_pk_fma_f32 v[38:39], v[10:11], v[84:85], v[38:39] op_sel_hi:[1,0,1]
	v_pk_fma_f32 v[40:41], v[10:11], v[84:85], v[40:41] op_sel:[0,1,0] op_sel_hi:[1,1,1]
	v_pk_fma_f32 v[38:39], v[12:13], v[86:87], v[38:39] op_sel_hi:[1,0,1]
	v_pk_fma_f32 v[40:41], v[12:13], v[86:87], v[40:41] op_sel:[0,1,0] op_sel_hi:[1,1,1]
	s_waitcnt lgkmcnt(3)
	v_pk_fma_f32 v[38:39], v[14:15], v[88:89], v[38:39] op_sel_hi:[1,0,1]
	v_pk_fma_f32 v[40:41], v[14:15], v[88:89], v[40:41] op_sel:[0,1,0] op_sel_hi:[1,1,1]
	v_pk_fma_f32 v[38:39], v[16:17], v[90:91], v[38:39] op_sel_hi:[1,0,1]
	v_pk_fma_f32 v[40:41], v[16:17], v[90:91], v[40:41] op_sel:[0,1,0] op_sel_hi:[1,1,1]
	s_waitcnt lgkmcnt(2)
	v_pk_fma_f32 v[38:39], v[18:19], v[92:93], v[38:39] op_sel_hi:[1,0,1]
	v_pk_fma_f32 v[40:41], v[18:19], v[92:93], v[40:41] op_sel:[0,1,0] op_sel_hi:[1,1,1]
	v_pk_fma_f32 v[38:39], v[20:21], v[94:95], v[38:39] op_sel_hi:[1,0,1]
	v_pk_fma_f32 v[40:41], v[20:21], v[94:95], v[40:41] op_sel:[0,1,0] op_sel_hi:[1,1,1]
	s_waitcnt lgkmcnt(0)
	v_mul_f32_e32 v51, v100, v50
	v_add_f32_dpp v38, v38, v38 row_ror:8 row_mask:0xf bank_mask:0x3 bound_ctrl:1
	v_add_f32_dpp v39, v39, v39 row_ror:8 row_mask:0xf bank_mask:0x3 bound_ctrl:1
	v_add_f32_dpp v38, v40, v40 row_ror:8 row_mask:0xf bank_mask:0xc bound_ctrl:1
	v_add_f32_dpp v39, v41, v41 row_ror:8 row_mask:0xf bank_mask:0xc bound_ctrl:1
	ds_read_b128 v[56:59], v2 offset:35072
	v_add_f32_dpp v38, v38, v38 row_half_mirror row_mask:0xf bank_mask:0x5 bound_ctrl:1
	v_add_f32_dpp v38, v39, v39 row_half_mirror row_mask:0xf bank_mask:0xa bound_ctrl:1
	ds_read_b128 v[60:63], v2 offset:35328
	ds_read_b128 v[64:67], v2 offset:35584
	v_add_f32_dpp v38, v38, v38 quad_perm:[1,0,3,2] row_mask:0xf bank_mask:0xf bound_ctrl:1
	ds_read_b128 v[68:71], v2 offset:35840
	ds_read_b64 v[72:73], v3 offset:45824
	v_add_f32_dpp v38, v38, v38 quad_perm:[2,3,0,1] row_mask:0xf bank_mask:0xf bound_ctrl:1
	ds_read_b128 v[76:79], v1 offset:47392
	v_cmp_gt_f32_e32 vcc, 0x2b8cbccc, v51
	v_fmac_f32_dpp v96, -v38, v51 row_newbcast:0 row_mask:0xf bank_mask:0xf bound_ctrl:1
	v_fmac_f32_dpp v97, -v38, v51 row_newbcast:4 row_mask:0xf bank_mask:0xf bound_ctrl:1
	v_pk_mul_f32 v[44:45], v[96:97], v[100:101] op_sel:[0,1] op_sel_hi:[1,1]
	v_pk_mul_f32 v[48:49], v[44:45], v[102:103] op_sel_hi:[1,0]
	v_rcp_f32_e32 v52, v51
	s_add_u32 s14, s14, 0x1000
	s_addc_u32 s15, s15, 0
	v_fmac_f32_dpp v48, v38, v51 row_newbcast:8 row_mask:0xf bank_mask:0xf bound_ctrl:1
	v_fmac_f32_dpp v49, v38, v51 row_newbcast:12 row_mask:0xf bank_mask:0xf bound_ctrl:1
	s_cbranch_vccnz .Lgd2_rare2_1
.Lgd2_back2_1:
	v_cvt_pk_bf16_f32 v54, v48, v49
	v_pk_mul_f32 v[46:47], v[44:45], v[52:53] op_sel_hi:[1,0]
	v_pk_fma_f32 v[6:7], v[80:81], v[46:47], v[6:7] op_sel_hi:[0,1,1]
	v_pk_fma_f32 v[8:9], v[82:83], v[46:47], v[8:9] op_sel_hi:[0,1,1]
	v_pk_fma_f32 v[10:11], v[84:85], v[46:47], v[10:11] op_sel_hi:[0,1,1]
	v_pk_fma_f32 v[12:13], v[86:87], v[46:47], v[12:13] op_sel_hi:[0,1,1]
	v_pk_fma_f32 v[14:15], v[88:89], v[46:47], v[14:15] op_sel_hi:[0,1,1]
	v_pk_fma_f32 v[16:17], v[90:91], v[46:47], v[16:17] op_sel_hi:[0,1,1]
	v_pk_fma_f32 v[18:19], v[92:93], v[46:47], v[18:19] op_sel_hi:[0,1,1]
	v_pk_fma_f32 v[20:21], v[94:95], v[46:47], v[20:21] op_sel_hi:[0,1,1]
	s_mov_b64 exec, s[18:19]
	global_store_dword v154, v54, s[14:15] offset:-4096
	s_mov_b64 exec, -1
	s_waitcnt lgkmcnt(5)
	v_pk_mul_f32 v[38:39], v[6:7], v[56:57] op_sel_hi:[1,0]
	v_pk_mul_f32 v[40:41], v[6:7], v[56:57] op_sel:[0,1] op_sel_hi:[1,1]
	v_pk_fma_f32 v[38:39], v[8:9], v[58:59], v[38:39] op_sel_hi:[1,0,1]
	v_pk_fma_f32 v[40:41], v[8:9], v[58:59], v[40:41] op_sel:[0,1,0] op_sel_hi:[1,1,1]
	s_waitcnt lgkmcnt(4)
	v_pk_fma_f32 v[38:39], v[10:11], v[60:61], v[38:39] op_sel_hi:[1,0,1]
	v_pk_fma_f32 v[40:41], v[10:11], v[60:61], v[40:41] op_sel:[0,1,0] op_sel_hi:[1,1,1]
	v_pk_fma_f32 v[38:39], v[12:13], v[62:63], v[38:39] op_sel_hi:[1,0,1]
	v_pk_fma_f32 v[40:41], v[12:13], v[62:63], v[40:41] op_sel:[0,1,0] op_sel_hi:[1,1,1]
	s_waitcnt lgkmcnt(3)
	v_pk_fma_f32 v[38:39], v[14:15], v[64:65], v[38:39] op_sel_hi:[1,0,1]
	v_pk_fma_f32 v[40:41], v[14:15], v[64:65], v[40:41] op_sel:[0,1,0] op_sel_hi:[1,1,1]
	v_pk_fma_f32 v[38:39], v[16:17], v[66:67], v[38:39] op_sel_hi:[1,0,1]
	v_pk_fma_f32 v[40:41], v[16:17], v[66:67], v[40:41] op_sel:[0,1,0] op_sel_hi:[1,1,1]
	s_waitcnt lgkmcnt(2)
	v_pk_fma_f32 v[38:39], v[18:19], v[68:69], v[38:39] op_sel_hi:[1,0,1]
	v_pk_fma_f32 v[40:41], v[18:19], v[68:69], v[40:41] op_sel:[0,1,0] op_sel_hi:[1,1,1]
	v_pk_fma_f32 v[38:39], v[20:21], v[70:71], v[38:39] op_sel_hi:[1,0,1]
	v_pk_fma_f32 v[40:41], v[20:21], v[70:71], v[40:41] op_sel:[0,1,0] op_sel_hi:[1,1,1]
	s_waitcnt lgkmcnt(0)
	v_mul_f32_e32 v50, v76, v51
	v_add_f32_dpp v38, v38, v38 row_ror:8 row_mask:0xf bank_mask:0x3 bound_ctrl:1
	v_add_f32_dpp v39, v39, v39 row_ror:8 row_mask:0xf bank_mask:0x3 bound_ctrl:1
	v_add_f32_dpp v38, v40, v40 row_ror:8 row_mask:0xf bank_mask:0xc bound_ctrl:1
	v_add_f32_dpp v39, v41, v41 row_ror:8 row_mask:0xf bank_mask:0xc bound_ctrl:1
	ds_read_b128 v[80:83], v2 offset:36096
	v_add_f32_dpp v38, v38, v38 row_half_mirror row_mask:0xf bank_mask:0x5 bound_ctrl:1
	v_add_f32_dpp v38, v39, v39 row_half_mirror row_mask:0xf bank_mask:0xa bound_ctrl:1
	ds_read_b128 v[84:87], v2 offset:36352
	ds_read_b128 v[88:91], v2 offset:36608
	v_add_f32_dpp v38, v38, v38 quad_perm:[1,0,3,2] row_mask:0xf bank_mask:0xf bound_ctrl:1
	ds_read_b128 v[92:95], v2 offset:36864
	ds_read_b64 v[96:97], v3 offset:46080
	v_add_f32_dpp v38, v38, v38 quad_perm:[2,3,0,1] row_mask:0xf bank_mask:0xf bound_ctrl:1
	ds_read_b128 v[100:103], v1 offset:47408
	v_cmp_gt_f32_e32 vcc, 0x2b8cbccc, v50
	v_fmac_f32_dpp v72, -v38, v50 row_newbcast:0 row_mask:0xf bank_mask:0xf bound_ctrl:1
	v_fmac_f32_dpp v73, -v38, v50 row_newbcast:4 row_mask:0xf bank_mask:0xf bound_ctrl:1
	v_pk_mul_f32 v[44:45], v[72:73], v[76:77] op_sel:[0,1] op_sel_hi:[1,1]
	v_pk_mul_f32 v[48:49], v[44:45], v[78:79] op_sel_hi:[1,0]
	v_rcp_f32_e32 v52, v50
	s_add_u32 s14, s14, 0x1000
	s_addc_u32 s15, s15, 0
	v_fmac_f32_dpp v48, v38, v50 row_newbcast:8 row_mask:0xf bank_mask:0xf bound_ctrl:1
	v_fmac_f32_dpp v49, v38, v50 row_newbcast:12 row_mask:0xf bank_mask:0xf bound_ctrl:1
	s_cbranch_vccnz .Lgd2_rare2_2
.Lgd2_back2_2:
	v_cvt_pk_bf16_f32 v54, v48, v49
	v_pk_mul_f32 v[46:47], v[44:45], v[52:53] op_sel_hi:[1,0]
	v_pk_fma_f32 v[6:7], v[56:57], v[46:47], v[6:7] op_sel_hi:[0,1,1]
	v_pk_fma_f32 v[8:9], v[58:59], v[46:47], v[8:9] op_sel_hi:[0,1,1]
	v_pk_fma_f32 v[10:11], v[60:61], v[46:47], v[10:11] op_sel_hi:[0,1,1]
	v_pk_fma_f32 v[12:13], v[62:63], v[46:47], v[12:13] op_sel_hi:[0,1,1]
	v_pk_fma_f32 v[14:15], v[64:65], v[46:47], v[14:15] op_sel_hi:[0,1,1]
	v_pk_fma_f32 v[16:17], v[66:67], v[46:47], v[16:17] op_sel_hi:[0,1,1]
	v_pk_fma_f32 v[18:19], v[68:69], v[46:47], v[18:19] op_sel_hi:[0,1,1]
	v_pk_fma_f32 v[20:21], v[70:71], v[46:47], v[20:21] op_sel_hi:[0,1,1]
	s_mov_b64 exec, s[18:19]
	global_store_dword v154, v54, s[14:15] offset:-4096
	s_mov_b64 exec, -1
	s_waitcnt lgkmcnt(5)
	v_pk_mul_f32 v[38:39], v[6:7], v[80:81] op_sel_hi:[1,0]
	v_pk_mul_f32 v[40:41], v[6:7], v[80:81] op_sel:[0,1] op_sel_hi:[1,1]
	v_pk_fma_f32 v[38:39], v[8:9], v[82:83], v[38:39] op_sel_hi:[1,0,1]
	v_pk_fma_f32 v[40:41], v[8:9], v[82:83], v[40:41] op_sel:[0,1,0] op_sel_hi:[1,1,1]
	s_waitcnt lgkmcnt(4)
	v_pk_fma_f32 v[38:39], v[10:11], v[84:85], v[38:39] op_sel_hi:[1,0,1]
	v_pk_fma_f32 v[40:41], v[10:11], v[84:85], v[40:41] op_sel:[0,1,0] op_sel_hi:[1,1,1]
	v_pk_fma_f32 v[38:39], v[12:13], v[86:87], v[38:39] op_sel_hi:[1,0,1]
	v_pk_fma_f32 v[40:41], v[12:13], v[86:87], v[40:41] op_sel:[0,1,0] op_sel_hi:[1,1,1]
	s_waitcnt lgkmcnt(3)
	v_pk_fma_f32 v[38:39], v[14:15], v[88:89], v[38:39] op_sel_hi:[1,0,1]
	v_pk_fma_f32 v[40:41], v[14:15], v[88:89], v[40:41] op_sel:[0,1,0] op_sel_hi:[1,1,1]
	v_pk_fma_f32 v[38:39], v[16:17], v[90:91], v[38:39] op_sel_hi:[1,0,1]
	v_pk_fma_f32 v[40:41], v[16:17], v[90:91], v[40:41] op_sel:[0,1,0] op_sel_hi:[1,1,1]
	s_waitcnt lgkmcnt(2)
	v_pk_fma_f32 v[38:39], v[18:19], v[92:93], v[38:39] op_sel_hi:[1,0,1]
	v_pk_fma_f32 v[40:41], v[18:19], v[92:93], v[40:41] op_sel:[0,1,0] op_sel_hi:[1,1,1]
	v_pk_fma_f32 v[38:39], v[20:21], v[94:95], v[38:39] op_sel_hi:[1,0,1]
	v_pk_fma_f32 v[40:41], v[20:21], v[94:95], v[40:41] op_sel:[0,1,0] op_sel_hi:[1,1,1]
	s_waitcnt lgkmcnt(0)
	v_mul_f32_e32 v51, v100, v50
	v_add_f32_dpp v38, v38, v38 row_ror:8 row_mask:0xf bank_mask:0x3 bound_ctrl:1
	v_add_f32_dpp v39, v39, v39 row_ror:8 row_mask:0xf bank_mask:0x3 bound_ctrl:1
	v_add_f32_dpp v38, v40, v40 row_ror:8 row_mask:0xf bank_mask:0xc bound_ctrl:1
	v_add_f32_dpp v39, v41, v41 row_ror:8 row_mask:0xf bank_mask:0xc bound_ctrl:1
	ds_read_b128 v[56:59], v2 offset:37120
	v_add_f32_dpp v38, v38, v38 row_half_mirror row_mask:0xf bank_mask:0x5 bound_ctrl:1
	v_add_f32_dpp v38, v39, v39 row_half_mirror row_mask:0xf bank_mask:0xa bound_ctrl:1
	ds_read_b128 v[60:63], v2 offset:37376
	ds_read_b128 v[64:67], v2 offset:37632
	v_add_f32_dpp v38, v38, v38 quad_perm:[1,0,3,2] row_mask:0xf bank_mask:0xf bound_ctrl:1
	ds_read_b128 v[68:71], v2 offset:37888
	ds_read_b64 v[72:73], v3 offset:46336
	v_add_f32_dpp v38, v38, v38 quad_perm:[2,3,0,1] row_mask:0xf bank_mask:0xf bound_ctrl:1
	ds_read_b128 v[76:79], v1 offset:47424
	v_cmp_gt_f32_e32 vcc, 0x2b8cbccc, v51
	v_fmac_f32_dpp v96, -v38, v51 row_newbcast:0 row_mask:0xf bank_mask:0xf bound_ctrl:1
	v_fmac_f32_dpp v97, -v38, v51 row_newbcast:4 row_mask:0xf bank_mask:0xf bound_ctrl:1
	v_pk_mul_f32 v[44:45], v[96:97], v[100:101] op_sel:[0,1] op_sel_hi:[1,1]
	v_pk_mul_f32 v[48:49], v[44:45], v[102:103] op_sel_hi:[1,0]
	v_rcp_f32_e32 v52, v51
	s_add_u32 s14, s14, 0x1000
	s_addc_u32 s15, s15, 0
	v_fmac_f32_dpp v48, v38, v51 row_newbcast:8 row_mask:0xf bank_mask:0xf bound_ctrl:1
	v_fmac_f32_dpp v49, v38, v51 row_newbcast:12 row_mask:0xf bank_mask:0xf bound_ctrl:1
	s_cbranch_vccnz .Lgd2_rare2_3
.Lgd2_back2_3:
	v_cvt_pk_bf16_f32 v54, v48, v49
	v_pk_mul_f32 v[46:47], v[44:45], v[52:53] op_sel_hi:[1,0]
	v_pk_fma_f32 v[6:7], v[80:81], v[46:47], v[6:7] op_sel_hi:[0,1,1]
	v_pk_fma_f32 v[8:9], v[82:83], v[46:47], v[8:9] op_sel_hi:[0,1,1]
	v_pk_fma_f32 v[10:11], v[84:85], v[46:47], v[10:11] op_sel_hi:[0,1,1]
	v_pk_fma_f32 v[12:13], v[86:87], v[46:47], v[12:13] op_sel_hi:[0,1,1]
	v_pk_fma_f32 v[14:15], v[88:89], v[46:47], v[14:15] op_sel_hi:[0,1,1]
	v_pk_fma_f32 v[16:17], v[90:91], v[46:47], v[16:17] op_sel_hi:[0,1,1]
	v_pk_fma_f32 v[18:19], v[92:93], v[46:47], v[18:19] op_sel_hi:[0,1,1]
	v_pk_fma_f32 v[20:21], v[94:95], v[46:47], v[20:21] op_sel_hi:[0,1,1]
	s_mov_b64 exec, s[18:19]
	global_store_dword v154, v54, s[14:15] offset:-4096
	s_mov_b64 exec, -1
	s_waitcnt lgkmcnt(5)
	v_pk_mul_f32 v[38:39], v[6:7], v[56:57] op_sel_hi:[1,0]
	v_pk_mul_f32 v[40:41], v[6:7], v[56:57] op_sel:[0,1] op_sel_hi:[1,1]
	v_pk_fma_f32 v[38:39], v[8:9], v[58:59], v[38:39] op_sel_hi:[1,0,1]
	v_pk_fma_f32 v[40:41], v[8:9], v[58:59], v[40:41] op_sel:[0,1,0] op_sel_hi:[1,1,1]
	s_waitcnt lgkmcnt(4)
	v_pk_fma_f32 v[38:39], v[10:11], v[60:61], v[38:39] op_sel_hi:[1,0,1]
	v_pk_fma_f32 v[40:41], v[10:11], v[60:61], v[40:41] op_sel:[0,1,0] op_sel_hi:[1,1,1]
	v_pk_fma_f32 v[38:39], v[12:13], v[62:63], v[38:39] op_sel_hi:[1,0,1]
	v_pk_fma_f32 v[40:41], v[12:13], v[62:63], v[40:41] op_sel:[0,1,0] op_sel_hi:[1,1,1]
	s_waitcnt lgkmcnt(3)
	v_pk_fma_f32 v[38:39], v[14:15], v[64:65], v[38:39] op_sel_hi:[1,0,1]
	v_pk_fma_f32 v[40:41], v[14:15], v[64:65], v[40:41] op_sel:[0,1,0] op_sel_hi:[1,1,1]
	v_pk_fma_f32 v[38:39], v[16:17], v[66:67], v[38:39] op_sel_hi:[1,0,1]
	v_pk_fma_f32 v[40:41], v[16:17], v[66:67], v[40:41] op_sel:[0,1,0] op_sel_hi:[1,1,1]
	s_waitcnt lgkmcnt(2)
	v_pk_fma_f32 v[38:39], v[18:19], v[68:69], v[38:39] op_sel_hi:[1,0,1]
	v_pk_fma_f32 v[40:41], v[18:19], v[68:69], v[40:41] op_sel:[0,1,0] op_sel_hi:[1,1,1]
	v_pk_fma_f32 v[38:39], v[20:21], v[70:71], v[38:39] op_sel_hi:[1,0,1]
	v_pk_fma_f32 v[40:41], v[20:21], v[70:71], v[40:41] op_sel:[0,1,0] op_sel_hi:[1,1,1]
	s_waitcnt lgkmcnt(0)
	v_mul_f32_e32 v50, v76, v51
	v_add_f32_dpp v38, v38, v38 row_ror:8 row_mask:0xf bank_mask:0x3 bound_ctrl:1
	v_add_f32_dpp v39, v39, v39 row_ror:8 row_mask:0xf bank_mask:0x3 bound_ctrl:1
	v_add_f32_dpp v38, v40, v40 row_ror:8 row_mask:0xf bank_mask:0xc bound_ctrl:1
	v_add_f32_dpp v39, v41, v41 row_ror:8 row_mask:0xf bank_mask:0xc bound_ctrl:1
	ds_read_b128 v[80:83], v2 offset:38144
	v_add_f32_dpp v38, v38, v38 row_half_mirror row_mask:0xf bank_mask:0x5 bound_ctrl:1
	v_add_f32_dpp v38, v39, v39 row_half_mirror row_mask:0xf bank_mask:0xa bound_ctrl:1
	ds_read_b128 v[84:87], v2 offset:38400
	ds_read_b128 v[88:91], v2 offset:38656
	v_add_f32_dpp v38, v38, v38 quad_perm:[1,0,3,2] row_mask:0xf bank_mask:0xf bound_ctrl:1
	ds_read_b128 v[92:95], v2 offset:38912
	ds_read_b64 v[96:97], v3 offset:46592
	v_add_f32_dpp v38, v38, v38 quad_perm:[2,3,0,1] row_mask:0xf bank_mask:0xf bound_ctrl:1
	ds_read_b128 v[100:103], v1 offset:47440
	v_cmp_gt_f32_e32 vcc, 0x2b8cbccc, v50
	v_fmac_f32_dpp v72, -v38, v50 row_newbcast:0 row_mask:0xf bank_mask:0xf bound_ctrl:1
	v_fmac_f32_dpp v73, -v38, v50 row_newbcast:4 row_mask:0xf bank_mask:0xf bound_ctrl:1
	v_pk_mul_f32 v[44:45], v[72:73], v[76:77] op_sel:[0,1] op_sel_hi:[1,1]
	v_pk_mul_f32 v[48:49], v[44:45], v[78:79] op_sel_hi:[1,0]
	v_rcp_f32_e32 v52, v50
	s_add_u32 s14, s14, 0x1000
	s_addc_u32 s15, s15, 0
	v_fmac_f32_dpp v48, v38, v50 row_newbcast:8 row_mask:0xf bank_mask:0xf bound_ctrl:1
	v_fmac_f32_dpp v49, v38, v50 row_newbcast:12 row_mask:0xf bank_mask:0xf bound_ctrl:1
	s_cbranch_vccnz .Lgd2_rare2_4
.Lgd2_back2_4:
	v_cvt_pk_bf16_f32 v54, v48, v49
	v_pk_mul_f32 v[46:47], v[44:45], v[52:53] op_sel_hi:[1,0]
	v_pk_fma_f32 v[6:7], v[56:57], v[46:47], v[6:7] op_sel_hi:[0,1,1]
	v_pk_fma_f32 v[8:9], v[58:59], v[46:47], v[8:9] op_sel_hi:[0,1,1]
	v_pk_fma_f32 v[10:11], v[60:61], v[46:47], v[10:11] op_sel_hi:[0,1,1]
	v_pk_fma_f32 v[12:13], v[62:63], v[46:47], v[12:13] op_sel_hi:[0,1,1]
	v_pk_fma_f32 v[14:15], v[64:65], v[46:47], v[14:15] op_sel_hi:[0,1,1]
	v_pk_fma_f32 v[16:17], v[66:67], v[46:47], v[16:17] op_sel_hi:[0,1,1]
	v_pk_fma_f32 v[18:19], v[68:69], v[46:47], v[18:19] op_sel_hi:[0,1,1]
	v_pk_fma_f32 v[20:21], v[70:71], v[46:47], v[20:21] op_sel_hi:[0,1,1]
	s_mov_b64 exec, s[18:19]
	global_store_dword v154, v54, s[14:15] offset:-4096
	s_mov_b64 exec, -1
	s_waitcnt lgkmcnt(5)
	v_pk_mul_f32 v[38:39], v[6:7], v[80:81] op_sel_hi:[1,0]
	v_pk_mul_f32 v[40:41], v[6:7], v[80:81] op_sel:[0,1] op_sel_hi:[1,1]
	v_pk_fma_f32 v[38:39], v[8:9], v[82:83], v[38:39] op_sel_hi:[1,0,1]
	v_pk_fma_f32 v[40:41], v[8:9], v[82:83], v[40:41] op_sel:[0,1,0] op_sel_hi:[1,1,1]
	s_waitcnt lgkmcnt(4)
	v_pk_fma_f32 v[38:39], v[10:11], v[84:85], v[38:39] op_sel_hi:[1,0,1]
	v_pk_fma_f32 v[40:41], v[10:11], v[84:85], v[40:41] op_sel:[0,1,0] op_sel_hi:[1,1,1]
	v_pk_fma_f32 v[38:39], v[12:13], v[86:87], v[38:39] op_sel_hi:[1,0,1]
	v_pk_fma_f32 v[40:41], v[12:13], v[86:87], v[40:41] op_sel:[0,1,0] op_sel_hi:[1,1,1]
	s_waitcnt lgkmcnt(3)
	v_pk_fma_f32 v[38:39], v[14:15], v[88:89], v[38:39] op_sel_hi:[1,0,1]
	v_pk_fma_f32 v[40:41], v[14:15], v[88:89], v[40:41] op_sel:[0,1,0] op_sel_hi:[1,1,1]
	v_pk_fma_f32 v[38:39], v[16:17], v[90:91], v[38:39] op_sel_hi:[1,0,1]
	v_pk_fma_f32 v[40:41], v[16:17], v[90:91], v[40:41] op_sel:[0,1,0] op_sel_hi:[1,1,1]
	s_waitcnt lgkmcnt(2)
	v_pk_fma_f32 v[38:39], v[18:19], v[92:93], v[38:39] op_sel_hi:[1,0,1]
	v_pk_fma_f32 v[40:41], v[18:19], v[92:93], v[40:41] op_sel:[0,1,0] op_sel_hi:[1,1,1]
	v_pk_fma_f32 v[38:39], v[20:21], v[94:95], v[38:39] op_sel_hi:[1,0,1]
	v_pk_fma_f32 v[40:41], v[20:21], v[94:95], v[40:41] op_sel:[0,1,0] op_sel_hi:[1,1,1]
	s_waitcnt lgkmcnt(0)
	v_mul_f32_e32 v51, v100, v50
	v_add_f32_dpp v38, v38, v38 row_ror:8 row_mask:0xf bank_mask:0x3 bound_ctrl:1
	v_add_f32_dpp v39, v39, v39 row_ror:8 row_mask:0xf bank_mask:0x3 bound_ctrl:1
	v_add_f32_dpp v38, v40, v40 row_ror:8 row_mask:0xf bank_mask:0xc bound_ctrl:1
	v_add_f32_dpp v39, v41, v41 row_ror:8 row_mask:0xf bank_mask:0xc bound_ctrl:1
	ds_read_b128 v[56:59], v2 offset:39168
	v_add_f32_dpp v38, v38, v38 row_half_mirror row_mask:0xf bank_mask:0x5 bound_ctrl:1
	v_add_f32_dpp v38, v39, v39 row_half_mirror row_mask:0xf bank_mask:0xa bound_ctrl:1
	ds_read_b128 v[60:63], v2 offset:39424
	ds_read_b128 v[64:67], v2 offset:39680
	v_add_f32_dpp v38, v38, v38 quad_perm:[1,0,3,2] row_mask:0xf bank_mask:0xf bound_ctrl:1
	ds_read_b128 v[68:71], v2 offset:39936
	ds_read_b64 v[72:73], v3 offset:46848
	v_add_f32_dpp v38, v38, v38 quad_perm:[2,3,0,1] row_mask:0xf bank_mask:0xf bound_ctrl:1
	ds_read_b128 v[76:79], v1 offset:47456
	v_cmp_gt_f32_e32 vcc, 0x2b8cbccc, v51
	v_fmac_f32_dpp v96, -v38, v51 row_newbcast:0 row_mask:0xf bank_mask:0xf bound_ctrl:1
	v_fmac_f32_dpp v97, -v38, v51 row_newbcast:4 row_mask:0xf bank_mask:0xf bound_ctrl:1
	v_pk_mul_f32 v[44:45], v[96:97], v[100:101] op_sel:[0,1] op_sel_hi:[1,1]
	v_pk_mul_f32 v[48:49], v[44:45], v[102:103] op_sel_hi:[1,0]
	v_rcp_f32_e32 v52, v51
	s_add_u32 s14, s14, 0x1000
	s_addc_u32 s15, s15, 0
	v_fmac_f32_dpp v48, v38, v51 row_newbcast:8 row_mask:0xf bank_mask:0xf bound_ctrl:1
	v_fmac_f32_dpp v49, v38, v51 row_newbcast:12 row_mask:0xf bank_mask:0xf bound_ctrl:1
	s_cbranch_vccnz .Lgd2_rare2_5
.Lgd2_back2_5:
	v_cvt_pk_bf16_f32 v54, v48, v49
	v_pk_mul_f32 v[46:47], v[44:45], v[52:53] op_sel_hi:[1,0]
	v_pk_fma_f32 v[6:7], v[80:81], v[46:47], v[6:7] op_sel_hi:[0,1,1]
	v_pk_fma_f32 v[8:9], v[82:83], v[46:47], v[8:9] op_sel_hi:[0,1,1]
	v_pk_fma_f32 v[10:11], v[84:85], v[46:47], v[10:11] op_sel_hi:[0,1,1]
	v_pk_fma_f32 v[12:13], v[86:87], v[46:47], v[12:13] op_sel_hi:[0,1,1]
	v_pk_fma_f32 v[14:15], v[88:89], v[46:47], v[14:15] op_sel_hi:[0,1,1]
	v_pk_fma_f32 v[16:17], v[90:91], v[46:47], v[16:17] op_sel_hi:[0,1,1]
	v_pk_fma_f32 v[18:19], v[92:93], v[46:47], v[18:19] op_sel_hi:[0,1,1]
	v_pk_fma_f32 v[20:21], v[94:95], v[46:47], v[20:21] op_sel_hi:[0,1,1]
	s_mov_b64 exec, s[18:19]
	global_store_dword v154, v54, s[14:15] offset:-4096
	s_mov_b64 exec, -1
	s_waitcnt lgkmcnt(5)
	v_pk_mul_f32 v[38:39], v[6:7], v[56:57] op_sel_hi:[1,0]
	v_pk_mul_f32 v[40:41], v[6:7], v[56:57] op_sel:[0,1] op_sel_hi:[1,1]
	v_pk_fma_f32 v[38:39], v[8:9], v[58:59], v[38:39] op_sel_hi:[1,0,1]
	v_pk_fma_f32 v[40:41], v[8:9], v[58:59], v[40:41] op_sel:[0,1,0] op_sel_hi:[1,1,1]
	s_waitcnt lgkmcnt(4)
	v_pk_fma_f32 v[38:39], v[10:11], v[60:61], v[38:39] op_sel_hi:[1,0,1]
	v_pk_fma_f32 v[40:41], v[10:11], v[60:61], v[40:41] op_sel:[0,1,0] op_sel_hi:[1,1,1]
	v_pk_fma_f32 v[38:39], v[12:13], v[62:63], v[38:39] op_sel_hi:[1,0,1]
	v_pk_fma_f32 v[40:41], v[12:13], v[62:63], v[40:41] op_sel:[0,1,0] op_sel_hi:[1,1,1]
	s_waitcnt lgkmcnt(3)
	v_pk_fma_f32 v[38:39], v[14:15], v[64:65], v[38:39] op_sel_hi:[1,0,1]
	v_pk_fma_f32 v[40:41], v[14:15], v[64:65], v[40:41] op_sel:[0,1,0] op_sel_hi:[1,1,1]
	v_pk_fma_f32 v[38:39], v[16:17], v[66:67], v[38:39] op_sel_hi:[1,0,1]
	v_pk_fma_f32 v[40:41], v[16:17], v[66:67], v[40:41] op_sel:[0,1,0] op_sel_hi:[1,1,1]
	s_waitcnt lgkmcnt(2)
	v_pk_fma_f32 v[38:39], v[18:19], v[68:69], v[38:39] op_sel_hi:[1,0,1]
	v_pk_fma_f32 v[40:41], v[18:19], v[68:69], v[40:41] op_sel:[0,1,0] op_sel_hi:[1,1,1]
	v_pk_fma_f32 v[38:39], v[20:21], v[70:71], v[38:39] op_sel_hi:[1,0,1]
	v_pk_fma_f32 v[40:41], v[20:21], v[70:71], v[40:41] op_sel:[0,1,0] op_sel_hi:[1,1,1]
	s_waitcnt lgkmcnt(0)
	v_mul_f32_e32 v50, v76, v51
	v_add_f32_dpp v38, v38, v38 row_ror:8 row_mask:0xf bank_mask:0x3 bound_ctrl:1
	v_add_f32_dpp v39, v39, v39 row_ror:8 row_mask:0xf bank_mask:0x3 bound_ctrl:1
	v_add_f32_dpp v38, v40, v40 row_ror:8 row_mask:0xf bank_mask:0xc bound_ctrl:1
	v_add_f32_dpp v39, v41, v41 row_ror:8 row_mask:0xf bank_mask:0xc bound_ctrl:1
	ds_read_b128 v[80:83], v2 offset:40192
	v_add_f32_dpp v38, v38, v38 row_half_mirror row_mask:0xf bank_mask:0x5 bound_ctrl:1
	v_add_f32_dpp v38, v39, v39 row_half_mirror row_mask:0xf bank_mask:0xa bound_ctrl:1
	ds_read_b128 v[84:87], v2 offset:40448
	ds_read_b128 v[88:91], v2 offset:40704
	v_add_f32_dpp v38, v38, v38 quad_perm:[1,0,3,2] row_mask:0xf bank_mask:0xf bound_ctrl:1
	ds_read_b128 v[92:95], v2 offset:40960
	ds_read_b64 v[96:97], v3 offset:47104
	v_add_f32_dpp v38, v38, v38 quad_perm:[2,3,0,1] row_mask:0xf bank_mask:0xf bound_ctrl:1
	ds_read_b128 v[100:103], v1 offset:47472
	v_cmp_gt_f32_e32 vcc, 0x2b8cbccc, v50
	v_fmac_f32_dpp v72, -v38, v50 row_newbcast:0 row_mask:0xf bank_mask:0xf bound_ctrl:1
	v_fmac_f32_dpp v73, -v38, v50 row_newbcast:4 row_mask:0xf bank_mask:0xf bound_ctrl:1
	v_pk_mul_f32 v[44:45], v[72:73], v[76:77] op_sel:[0,1] op_sel_hi:[1,1]
	v_pk_mul_f32 v[48:49], v[44:45], v[78:79] op_sel_hi:[1,0]
	v_rcp_f32_e32 v52, v50
	s_add_u32 s14, s14, 0x1000
	s_addc_u32 s15, s15, 0
	v_fmac_f32_dpp v48, v38, v50 row_newbcast:8 row_mask:0xf bank_mask:0xf bound_ctrl:1
	v_fmac_f32_dpp v49, v38, v50 row_newbcast:12 row_mask:0xf bank_mask:0xf bound_ctrl:1
	s_cbranch_vccnz .Lgd2_rare2_6
.Lgd2_back2_6:
	v_cvt_pk_bf16_f32 v54, v48, v49
	v_pk_mul_f32 v[46:47], v[44:45], v[52:53] op_sel_hi:[1,0]
	v_pk_fma_f32 v[6:7], v[56:57], v[46:47], v[6:7] op_sel_hi:[0,1,1]
	v_pk_fma_f32 v[8:9], v[58:59], v[46:47], v[8:9] op_sel_hi:[0,1,1]
	v_pk_fma_f32 v[10:11], v[60:61], v[46:47], v[10:11] op_sel_hi:[0,1,1]
	v_pk_fma_f32 v[12:13], v[62:63], v[46:47], v[12:13] op_sel_hi:[0,1,1]
	v_pk_fma_f32 v[14:15], v[64:65], v[46:47], v[14:15] op_sel_hi:[0,1,1]
	v_pk_fma_f32 v[16:17], v[66:67], v[46:47], v[16:17] op_sel_hi:[0,1,1]
	v_pk_fma_f32 v[18:19], v[68:69], v[46:47], v[18:19] op_sel_hi:[0,1,1]
	v_pk_fma_f32 v[20:21], v[70:71], v[46:47], v[20:21] op_sel_hi:[0,1,1]
	s_mov_b64 exec, s[18:19]
	global_store_dword v154, v54, s[14:15] offset:-4096
	s_mov_b64 exec, -1
	s_waitcnt lgkmcnt(5)
	v_pk_mul_f32 v[38:39], v[6:7], v[80:81] op_sel_hi:[1,0]
	v_pk_mul_f32 v[40:41], v[6:7], v[80:81] op_sel:[0,1] op_sel_hi:[1,1]
	v_pk_fma_f32 v[38:39], v[8:9], v[82:83], v[38:39] op_sel_hi:[1,0,1]
	v_pk_fma_f32 v[40:41], v[8:9], v[82:83], v[40:41] op_sel:[0,1,0] op_sel_hi:[1,1,1]
	s_waitcnt lgkmcnt(4)
	v_pk_fma_f32 v[38:39], v[10:11], v[84:85], v[38:39] op_sel_hi:[1,0,1]
	v_pk_fma_f32 v[40:41], v[10:11], v[84:85], v[40:41] op_sel:[0,1,0] op_sel_hi:[1,1,1]
	v_pk_fma_f32 v[38:39], v[12:13], v[86:87], v[38:39] op_sel_hi:[1,0,1]
	v_pk_fma_f32 v[40:41], v[12:13], v[86:87], v[40:41] op_sel:[0,1,0] op_sel_hi:[1,1,1]
	s_waitcnt lgkmcnt(3)
	v_pk_fma_f32 v[38:39], v[14:15], v[88:89], v[38:39] op_sel_hi:[1,0,1]
	v_pk_fma_f32 v[40:41], v[14:15], v[88:89], v[40:41] op_sel:[0,1,0] op_sel_hi:[1,1,1]
	v_pk_fma_f32 v[38:39], v[16:17], v[90:91], v[38:39] op_sel_hi:[1,0,1]
	v_pk_fma_f32 v[40:41], v[16:17], v[90:91], v[40:41] op_sel:[0,1,0] op_sel_hi:[1,1,1]
	s_waitcnt lgkmcnt(2)
	v_pk_fma_f32 v[38:39], v[18:19], v[92:93], v[38:39] op_sel_hi:[1,0,1]
	v_pk_fma_f32 v[40:41], v[18:19], v[92:93], v[40:41] op_sel:[0,1,0] op_sel_hi:[1,1,1]
	v_pk_fma_f32 v[38:39], v[20:21], v[94:95], v[38:39] op_sel_hi:[1,0,1]
	v_pk_fma_f32 v[40:41], v[20:21], v[94:95], v[40:41] op_sel:[0,1,0] op_sel_hi:[1,1,1]
	s_waitcnt lgkmcnt(0)
	v_mul_f32_e32 v51, v100, v50
	v_add_f32_dpp v38, v38, v38 row_ror:8 row_mask:0xf bank_mask:0x3 bound_ctrl:1
	v_add_f32_dpp v39, v39, v39 row_ror:8 row_mask:0xf bank_mask:0x3 bound_ctrl:1
	v_add_f32_dpp v38, v40, v40 row_ror:8 row_mask:0xf bank_mask:0xc bound_ctrl:1
	v_add_f32_dpp v39, v41, v41 row_ror:8 row_mask:0xf bank_mask:0xc bound_ctrl:1
	ds_read_b128 v[56:59], v2 offset:256
	v_add_f32_dpp v38, v38, v38 row_half_mirror row_mask:0xf bank_mask:0x5 bound_ctrl:1
	v_add_f32_dpp v38, v39, v39 row_half_mirror row_mask:0xf bank_mask:0xa bound_ctrl:1
	ds_read_b128 v[60:63], v2 offset:512
	ds_read_b128 v[64:67], v2 offset:768
	v_add_f32_dpp v38, v38, v38 quad_perm:[1,0,3,2] row_mask:0xf bank_mask:0xf bound_ctrl:1
	ds_read_b128 v[68:71], v2 offset:1024
	ds_read_b64 v[72:73], v3 offset:12544
	v_add_f32_dpp v38, v38, v38 quad_perm:[2,3,0,1] row_mask:0xf bank_mask:0xf bound_ctrl:1
	ds_read_b128 v[76:79], v1 offset:14592
	v_cmp_gt_f32_e32 vcc, 0x2b8cbccc, v51
	v_fmac_f32_dpp v96, -v38, v51 row_newbcast:0 row_mask:0xf bank_mask:0xf bound_ctrl:1
	v_fmac_f32_dpp v97, -v38, v51 row_newbcast:4 row_mask:0xf bank_mask:0xf bound_ctrl:1
	v_pk_mul_f32 v[44:45], v[96:97], v[100:101] op_sel:[0,1] op_sel_hi:[1,1]
	v_pk_mul_f32 v[48:49], v[44:45], v[102:103] op_sel_hi:[1,0]
	v_rcp_f32_e32 v52, v51
	s_add_u32 s14, s14, 0x1000
	s_addc_u32 s15, s15, 0
	v_fmac_f32_dpp v48, v38, v51 row_newbcast:8 row_mask:0xf bank_mask:0xf bound_ctrl:1
	v_fmac_f32_dpp v49, v38, v51 row_newbcast:12 row_mask:0xf bank_mask:0xf bound_ctrl:1
	s_cbranch_vccnz .Lgd2_rare2_7
.Lgd2_back2_7:
	v_cvt_pk_bf16_f32 v54, v48, v49
	v_pk_mul_f32 v[46:47], v[44:45], v[52:53] op_sel_hi:[1,0]
	v_pk_fma_f32 v[6:7], v[80:81], v[46:47], v[6:7] op_sel_hi:[0,1,1]
	v_pk_fma_f32 v[8:9], v[82:83], v[46:47], v[8:9] op_sel_hi:[0,1,1]
	v_pk_fma_f32 v[10:11], v[84:85], v[46:47], v[10:11] op_sel_hi:[0,1,1]
	v_pk_fma_f32 v[12:13], v[86:87], v[46:47], v[12:13] op_sel_hi:[0,1,1]
	v_pk_fma_f32 v[14:15], v[88:89], v[46:47], v[14:15] op_sel_hi:[0,1,1]
	v_pk_fma_f32 v[16:17], v[90:91], v[46:47], v[16:17] op_sel_hi:[0,1,1]
	v_pk_fma_f32 v[18:19], v[92:93], v[46:47], v[18:19] op_sel_hi:[0,1,1]
	v_pk_fma_f32 v[20:21], v[94:95], v[46:47], v[20:21] op_sel_hi:[0,1,1]
	s_mov_b64 exec, s[18:19]
	global_store_dword v154, v54, s[14:15] offset:-4096
	s_mov_b64 exec, -1
	s_waitcnt vmcnt(8)
	v_lshlrev_b32_e32 v116, 16, v108
	v_lshlrev_b32_e32 v117, 16, v109
	v_and_b32_e32 v118, s17, v108
	v_and_b32_e32 v119, s17, v109
	v_lshlrev_b32_e32 v120, 16, v110
	v_and_b32_e32 v121, s17, v110
	v_lshlrev_b32_e32 v122, 16, v111
	v_and_b32_e32 v123, s17, v111
	v_lshlrev_b32_e32 v124, 16, v112
	v_and_b32_e32 v125, s17, v112
	ds_write_b128 v32, v[116:119] offset:16640
	ds_write_b64 v33, v[120:121] offset:16640
	ds_write_b64 v34, v[122:123] offset:16640
	ds_write_b64 v34, v[124:125] offset:16768
	ds_write_b32 v35, v113 offset:16640
	s_add_i32 s16, s16, 8
	s_waitcnt lgkmcnt(0)
	s_barrier
	s_cmpk_lt_u32 s16, 0x800
	s_cbranch_scc1 .Lgd2_loop
